# GEMM loops: drop the mid-burst s_setprio 0/1 pair and the redundant lgkmcnt(0) after each barrier (bit-identical)
# speedup vs baseline: 1.0052x; 1.0052x over previous
.LBB0_182:
	ds_read_b128 v[144:147], v153
	ds_read_b128 v[156:159], v153 offset:1024
	ds_read_b128 v[160:163], v153 offset:2048
	ds_read_b128 v[164:167], v153 offset:3072
	ds_read_b128 v[168:171], v154
	ds_read_b128 v[172:175], v154 offset:1024
	ds_read_b128 v[176:179], v154 offset:2048
	ds_read_b128 v[180:183], v154 offset:3072
	s_add_u32 s30, s72, 0xfff00080
	s_addc_u32 s31, s73, -1
	s_cmp_eq_u32 s41, 60
	s_cselect_b32 s31, s13, s31
	s_cselect_b32 s30, s37, s30
	s_cselect_b32 s75, s11, s40
	s_cselect_b32 s74, s38, s39
	v_lshl_add_u64 v[216:217], s[72:73], 0, v[136:137]
	s_add_i32 m0, s29, 0xc000
	ds_read_b128 v[184:187], v155
	ds_read_b128 v[188:191], v155 offset:1024
	ds_read_b128 v[192:195], v155 offset:2048
	ds_read_b128 v[196:199], v155 offset:3072
	ds_read_b128 v[200:203], v155 offset:4096
	ds_read_b128 v[204:207], v155 offset:5120
	ds_read_b128 v[208:211], v155 offset:6144
	ds_read_b128 v[212:215], v155 offset:7168
	global_load_lds_dwordx4 v[216:217], off
	v_lshl_add_u64 v[216:217], s[72:73], 0, v[138:139]
	s_add_i32 m0, s29, 0xe000
	s_nop 0
	global_load_lds_dwordx4 v[216:217], off
	s_waitcnt vmcnt(8)
	s_waitcnt lgkmcnt(0)
	s_barrier
	s_setprio 1
	v_mfma_f32_16x16x32_bf16 v[124:127], v[144:147], v[184:187], v[124:127]
	v_mfma_f32_16x16x32_bf16 v[120:123], v[160:163], v[184:187], v[120:123]
	v_mfma_f32_16x16x32_bf16 v[108:111], v[144:147], v[192:195], v[108:111]
	v_mfma_f32_16x16x32_bf16 v[104:107], v[160:163], v[192:195], v[104:107]
	v_mfma_f32_16x16x32_bf16 v[92:95], v[144:147], v[200:203], v[92:95]
	v_mfma_f32_16x16x32_bf16 v[88:91], v[160:163], v[200:203], v[88:91]
	v_mfma_f32_16x16x32_bf16 v[76:79], v[144:147], v[208:211], v[76:79]
	v_mfma_f32_16x16x32_bf16 v[72:75], v[160:163], v[208:211], v[72:75]
	v_mfma_f32_16x16x32_bf16 v[124:127], v[156:159], v[188:191], v[124:127]
	v_mfma_f32_16x16x32_bf16 v[120:123], v[164:167], v[188:191], v[120:123]
	v_mfma_f32_16x16x32_bf16 v[108:111], v[156:159], v[196:199], v[108:111]
	v_mfma_f32_16x16x32_bf16 v[104:107], v[164:167], v[196:199], v[104:107]
	v_mfma_f32_16x16x32_bf16 v[92:95], v[156:159], v[204:207], v[92:95]
	v_mfma_f32_16x16x32_bf16 v[88:91], v[164:167], v[204:207], v[88:91]
	v_mfma_f32_16x16x32_bf16 v[76:79], v[156:159], v[212:215], v[76:79]
	v_mfma_f32_16x16x32_bf16 v[72:75], v[164:167], v[212:215], v[72:75]
	v_mfma_f32_16x16x32_bf16 v[116:119], v[168:171], v[184:187], v[116:119]
	v_mfma_f32_16x16x32_bf16 v[112:115], v[176:179], v[184:187], v[112:115]
	v_mfma_f32_16x16x32_bf16 v[100:103], v[168:171], v[192:195], v[100:103]
	v_mfma_f32_16x16x32_bf16 v[96:99], v[176:179], v[192:195], v[96:99]
	v_mfma_f32_16x16x32_bf16 v[84:87], v[168:171], v[200:203], v[84:87]
	v_mfma_f32_16x16x32_bf16 v[80:83], v[176:179], v[200:203], v[80:83]
	v_mfma_f32_16x16x32_bf16 v[68:71], v[168:171], v[208:211], v[68:71]
	v_mfma_f32_16x16x32_bf16 v[64:67], v[176:179], v[208:211], v[64:67]
	v_mfma_f32_16x16x32_bf16 v[116:119], v[172:175], v[188:191], v[116:119]
	v_mfma_f32_16x16x32_bf16 v[112:115], v[180:183], v[188:191], v[112:115]
	v_mfma_f32_16x16x32_bf16 v[100:103], v[172:175], v[196:199], v[100:103]
	v_mfma_f32_16x16x32_bf16 v[96:99], v[180:183], v[196:199], v[96:99]
	v_mfma_f32_16x16x32_bf16 v[84:87], v[172:175], v[204:207], v[84:87]
	v_mfma_f32_16x16x32_bf16 v[80:83], v[180:183], v[204:207], v[80:83]
	v_mfma_f32_16x16x32_bf16 v[68:71], v[172:175], v[212:215], v[68:71]
	v_mfma_f32_16x16x32_bf16 v[64:67], v[180:183], v[212:215], v[64:67]
	s_setprio 0
	s_barrier
	s_add_i32 s42, s81, s28
	v_lshl_add_u64 v[216:217], s[74:75], 0, v[130:131]
	s_mov_b32 m0, s42
	ds_read_b128 v[184:187], v155 offset:16384
	ds_read_b128 v[188:191], v155 offset:17408
	ds_read_b128 v[192:195], v155 offset:18432
	ds_read_b128 v[196:199], v155 offset:19456
	ds_read_b128 v[200:203], v155 offset:20480
	ds_read_b128 v[204:207], v155 offset:21504
	ds_read_b128 v[208:211], v155 offset:22528
	ds_read_b128 v[212:215], v155 offset:23552
	global_load_lds_dwordx4 v[216:217], off
	s_add_i32 m0, s42, 0x2000
	s_add_u32 s42, s74, 0x100000
	v_lshl_add_u64 v[218:219], s[74:75], 0, v[134:135]
	s_addc_u32 s43, s75, 0
	s_add_i32 s44, s82, s28
	global_load_lds_dwordx4 v[218:219], off
	v_lshl_add_u64 v[220:221], s[42:43], 0, v[130:131]
	s_mov_b32 m0, s44
	v_lshl_add_u64 v[222:223], s[30:31], 0, v[132:133]
	global_load_lds_dwordx4 v[220:221], off
	v_lshl_add_u64 v[220:221], s[42:43], 0, v[134:135]
	s_add_i32 m0, s44, 0x2000
	s_nop 0
	global_load_lds_dwordx4 v[220:221], off
	v_lshl_add_u64 v[220:221], s[30:31], 0, v[128:129]
	s_mov_b32 m0, s29
	s_nop 0
	global_load_lds_dwordx4 v[220:221], off
	s_mov_b32 m0, s33
	s_nop 0
	global_load_lds_dwordx4 v[222:223], off
	s_waitcnt vmcnt(8)
	s_waitcnt lgkmcnt(0)
	s_barrier
	s_setprio 1
	v_mfma_f32_16x16x32_bf16 v[60:63], v[144:147], v[184:187], v[60:63]
	v_mfma_f32_16x16x32_bf16 v[56:59], v[160:163], v[184:187], v[56:59]
	v_mfma_f32_16x16x32_bf16 v[44:47], v[144:147], v[192:195], v[44:47]
	v_mfma_f32_16x16x32_bf16 v[40:43], v[160:163], v[192:195], v[40:43]
	v_mfma_f32_16x16x32_bf16 v[28:31], v[144:147], v[200:203], v[28:31]
	v_mfma_f32_16x16x32_bf16 v[24:27], v[160:163], v[200:203], v[24:27]
	v_mfma_f32_16x16x32_bf16 v[12:15], v[144:147], v[208:211], v[12:15]
	v_mfma_f32_16x16x32_bf16 v[8:11], v[160:163], v[208:211], v[8:11]
	v_mfma_f32_16x16x32_bf16 v[60:63], v[156:159], v[188:191], v[60:63]
	v_mfma_f32_16x16x32_bf16 v[56:59], v[164:167], v[188:191], v[56:59]
	v_mfma_f32_16x16x32_bf16 v[44:47], v[156:159], v[196:199], v[44:47]
	v_mfma_f32_16x16x32_bf16 v[40:43], v[164:167], v[196:199], v[40:43]
	v_mfma_f32_16x16x32_bf16 v[28:31], v[156:159], v[204:207], v[28:31]
	v_mfma_f32_16x16x32_bf16 v[24:27], v[164:167], v[204:207], v[24:27]
	v_mfma_f32_16x16x32_bf16 v[12:15], v[156:159], v[212:215], v[12:15]
	v_mfma_f32_16x16x32_bf16 v[8:11], v[164:167], v[212:215], v[8:11]
	v_mfma_f32_16x16x32_bf16 v[52:55], v[168:171], v[184:187], v[52:55]
	v_mfma_f32_16x16x32_bf16 v[48:51], v[176:179], v[184:187], v[48:51]
	v_mfma_f32_16x16x32_bf16 v[36:39], v[168:171], v[192:195], v[36:39]
	v_mfma_f32_16x16x32_bf16 v[32:35], v[176:179], v[192:195], v[32:35]
	v_mfma_f32_16x16x32_bf16 v[20:23], v[168:171], v[200:203], v[20:23]
	v_mfma_f32_16x16x32_bf16 v[16:19], v[176:179], v[200:203], v[16:19]
	v_mfma_f32_16x16x32_bf16 v[4:7], v[168:171], v[208:211], v[4:7]
	v_mfma_f32_16x16x32_bf16 v[0:3], v[176:179], v[208:211], v[0:3]
	v_mfma_f32_16x16x32_bf16 v[52:55], v[172:175], v[188:191], v[52:55]
	v_mfma_f32_16x16x32_bf16 v[48:51], v[180:183], v[188:191], v[48:51]
	v_mfma_f32_16x16x32_bf16 v[36:39], v[172:175], v[196:199], v[36:39]
	v_mfma_f32_16x16x32_bf16 v[32:35], v[180:183], v[196:199], v[32:35]
	v_mfma_f32_16x16x32_bf16 v[20:23], v[172:175], v[204:207], v[20:23]
	v_mfma_f32_16x16x32_bf16 v[16:19], v[180:183], v[204:207], v[16:19]
	v_mfma_f32_16x16x32_bf16 v[4:7], v[172:175], v[212:215], v[4:7]
	v_mfma_f32_16x16x32_bf16 v[0:3], v[180:183], v[212:215], v[0:3]
	s_setprio 0
	s_barrier
	s_add_i32 s42, 0, 0x18000
	s_add_i32 s43, 0, 0x1c000
	v_add_u32_e32 v164, s42, v151
	v_add_u32_e32 v180, s43, v151
	ds_read_b128 v[144:147], v164
	ds_read_b128 v[156:159], v164 offset:1024
	ds_read_b128 v[160:163], v164 offset:2048
	ds_read_b128 v[164:167], v164 offset:3072
	ds_read_b128 v[168:171], v180
	ds_read_b128 v[172:175], v180 offset:1024
	ds_read_b128 v[176:179], v180 offset:2048
	ds_read_b128 v[180:183], v180 offset:3072
	s_add_u32 s30, s30, 0x100000
	s_addc_u32 s31, s31, 0
	s_mov_b32 m0, s53
	v_lshl_add_u64 v[224:225], s[30:31], 0, v[128:129]
	ds_read_b128 v[184:187], v155 offset:32768
	ds_read_b128 v[188:191], v155 offset:33792
	ds_read_b128 v[192:195], v155 offset:34816
	ds_read_b128 v[196:199], v155 offset:35840
	ds_read_b128 v[200:203], v155 offset:36864
	ds_read_b128 v[204:207], v155 offset:37888
	ds_read_b128 v[208:211], v155 offset:38912
	ds_read_b128 v[212:215], v155 offset:39936
	global_load_lds_dwordx4 v[224:225], off
	v_lshl_add_u64 v[224:225], s[30:31], 0, v[132:133]
	s_mov_b32 m0, s76
	s_nop 0
	global_load_lds_dwordx4 v[224:225], off
	s_waitcnt vmcnt(8)
	s_waitcnt lgkmcnt(0)
	s_barrier
	s_setprio 1
	v_mfma_f32_16x16x32_bf16 v[124:127], v[144:147], v[184:187], v[124:127]
	v_mfma_f32_16x16x32_bf16 v[120:123], v[160:163], v[184:187], v[120:123]
	v_mfma_f32_16x16x32_bf16 v[108:111], v[144:147], v[192:195], v[108:111]
	v_mfma_f32_16x16x32_bf16 v[104:107], v[160:163], v[192:195], v[104:107]
	v_mfma_f32_16x16x32_bf16 v[92:95], v[144:147], v[200:203], v[92:95]
	v_mfma_f32_16x16x32_bf16 v[88:91], v[160:163], v[200:203], v[88:91]
	v_mfma_f32_16x16x32_bf16 v[76:79], v[144:147], v[208:211], v[76:79]
	v_mfma_f32_16x16x32_bf16 v[72:75], v[160:163], v[208:211], v[72:75]
	v_mfma_f32_16x16x32_bf16 v[124:127], v[156:159], v[188:191], v[124:127]
	v_mfma_f32_16x16x32_bf16 v[120:123], v[164:167], v[188:191], v[120:123]
	v_mfma_f32_16x16x32_bf16 v[108:111], v[156:159], v[196:199], v[108:111]
	v_mfma_f32_16x16x32_bf16 v[104:107], v[164:167], v[196:199], v[104:107]
	v_mfma_f32_16x16x32_bf16 v[92:95], v[156:159], v[204:207], v[92:95]
	v_mfma_f32_16x16x32_bf16 v[88:91], v[164:167], v[204:207], v[88:91]
	v_mfma_f32_16x16x32_bf16 v[76:79], v[156:159], v[212:215], v[76:79]
	v_mfma_f32_16x16x32_bf16 v[72:75], v[164:167], v[212:215], v[72:75]
	v_mfma_f32_16x16x32_bf16 v[116:119], v[168:171], v[184:187], v[116:119]
	v_mfma_f32_16x16x32_bf16 v[112:115], v[176:179], v[184:187], v[112:115]
	v_mfma_f32_16x16x32_bf16 v[100:103], v[168:171], v[192:195], v[100:103]
	v_mfma_f32_16x16x32_bf16 v[96:99], v[176:179], v[192:195], v[96:99]
	v_mfma_f32_16x16x32_bf16 v[84:87], v[168:171], v[200:203], v[84:87]
	v_mfma_f32_16x16x32_bf16 v[80:83], v[176:179], v[200:203], v[80:83]
	v_mfma_f32_16x16x32_bf16 v[68:71], v[168:171], v[208:211], v[68:71]
	v_mfma_f32_16x16x32_bf16 v[64:67], v[176:179], v[208:211], v[64:67]
	v_mfma_f32_16x16x32_bf16 v[116:119], v[172:175], v[188:191], v[116:119]
	v_mfma_f32_16x16x32_bf16 v[112:115], v[180:183], v[188:191], v[112:115]
	v_mfma_f32_16x16x32_bf16 v[100:103], v[172:175], v[196:199], v[100:103]
	v_mfma_f32_16x16x32_bf16 v[96:99], v[180:183], v[196:199], v[96:99]
	v_mfma_f32_16x16x32_bf16 v[84:87], v[172:175], v[204:207], v[84:87]
	v_mfma_f32_16x16x32_bf16 v[80:83], v[180:183], v[204:207], v[80:83]
	v_mfma_f32_16x16x32_bf16 v[68:71], v[172:175], v[212:215], v[68:71]
	v_mfma_f32_16x16x32_bf16 v[64:67], v[180:183], v[212:215], v[64:67]
	s_setprio 0
	s_barrier
	s_add_i32 s30, s42, s28
	v_lshl_add_u64 v[216:217], v[216:217], 0, s[4:5]
	s_mov_b32 m0, s30
	ds_read_b128 v[184:187], v155 offset:49152
	ds_read_b128 v[188:191], v155 offset:50176
	ds_read_b128 v[192:195], v155 offset:51200
	ds_read_b128 v[196:199], v155 offset:52224
	ds_read_b128 v[200:203], v155 offset:53248
	ds_read_b128 v[204:207], v155 offset:54272
	ds_read_b128 v[208:211], v155 offset:55296
	ds_read_b128 v[212:215], v155 offset:56320
	global_load_lds_dwordx4 v[216:217], off
	s_add_i32 m0, s30, 0x2000
	s_add_u32 s30, s74, 0x100080
	v_lshl_add_u64 v[216:217], v[218:219], 0, s[4:5]
	s_addc_u32 s31, s75, 0
	s_add_i32 s42, s43, s28
	global_load_lds_dwordx4 v[216:217], off
	v_lshl_add_u64 v[216:217], s[30:31], 0, v[130:131]
	s_mov_b32 m0, s42
	s_nop 0
	global_load_lds_dwordx4 v[216:217], off
	v_lshl_add_u64 v[216:217], s[30:31], 0, v[134:135]
	s_add_i32 m0, s42, 0x2000
	s_nop 0
	global_load_lds_dwordx4 v[216:217], off
	v_lshl_add_u64 v[216:217], v[220:221], 0, s[4:5]
	s_mov_b32 m0, s78
	s_nop 0
	global_load_lds_dwordx4 v[216:217], off
	v_lshl_add_u64 v[216:217], v[222:223], 0, s[4:5]
	s_mov_b32 m0, s79
	s_nop 0
	global_load_lds_dwordx4 v[216:217], off
	s_waitcnt vmcnt(8)
	s_waitcnt lgkmcnt(0)
	s_barrier
	s_setprio 1
	v_mfma_f32_16x16x32_bf16 v[60:63], v[144:147], v[184:187], v[60:63]
	v_mfma_f32_16x16x32_bf16 v[56:59], v[160:163], v[184:187], v[56:59]
	v_mfma_f32_16x16x32_bf16 v[44:47], v[144:147], v[192:195], v[44:47]
	v_mfma_f32_16x16x32_bf16 v[40:43], v[160:163], v[192:195], v[40:43]
	v_mfma_f32_16x16x32_bf16 v[28:31], v[144:147], v[200:203], v[28:31]
	v_mfma_f32_16x16x32_bf16 v[24:27], v[160:163], v[200:203], v[24:27]
	v_mfma_f32_16x16x32_bf16 v[12:15], v[144:147], v[208:211], v[12:15]
	v_mfma_f32_16x16x32_bf16 v[8:11], v[160:163], v[208:211], v[8:11]
	v_mfma_f32_16x16x32_bf16 v[60:63], v[156:159], v[188:191], v[60:63]
	v_mfma_f32_16x16x32_bf16 v[56:59], v[164:167], v[188:191], v[56:59]
	v_mfma_f32_16x16x32_bf16 v[44:47], v[156:159], v[196:199], v[44:47]
	v_mfma_f32_16x16x32_bf16 v[40:43], v[164:167], v[196:199], v[40:43]
	v_mfma_f32_16x16x32_bf16 v[28:31], v[156:159], v[204:207], v[28:31]
	v_mfma_f32_16x16x32_bf16 v[24:27], v[164:167], v[204:207], v[24:27]
	v_mfma_f32_16x16x32_bf16 v[12:15], v[156:159], v[212:215], v[12:15]
	v_mfma_f32_16x16x32_bf16 v[8:11], v[164:167], v[212:215], v[8:11]
	v_mfma_f32_16x16x32_bf16 v[52:55], v[168:171], v[184:187], v[52:55]
	v_mfma_f32_16x16x32_bf16 v[48:51], v[176:179], v[184:187], v[48:51]
	v_mfma_f32_16x16x32_bf16 v[36:39], v[168:171], v[192:195], v[36:39]
	v_mfma_f32_16x16x32_bf16 v[32:35], v[176:179], v[192:195], v[32:35]
	v_mfma_f32_16x16x32_bf16 v[20:23], v[168:171], v[200:203], v[20:23]
	v_mfma_f32_16x16x32_bf16 v[16:19], v[176:179], v[200:203], v[16:19]
	v_mfma_f32_16x16x32_bf16 v[4:7], v[168:171], v[208:211], v[4:7]
	v_mfma_f32_16x16x32_bf16 v[0:3], v[176:179], v[208:211], v[0:3]
	v_mfma_f32_16x16x32_bf16 v[52:55], v[172:175], v[188:191], v[52:55]
	v_mfma_f32_16x16x32_bf16 v[48:51], v[180:183], v[188:191], v[48:51]
	v_mfma_f32_16x16x32_bf16 v[36:39], v[172:175], v[196:199], v[36:39]
	v_mfma_f32_16x16x32_bf16 v[32:35], v[180:183], v[196:199], v[32:35]
	v_mfma_f32_16x16x32_bf16 v[20:23], v[172:175], v[204:207], v[20:23]
	v_mfma_f32_16x16x32_bf16 v[16:19], v[180:183], v[204:207], v[16:19]
	v_mfma_f32_16x16x32_bf16 v[4:7], v[172:175], v[212:215], v[4:7]
	v_mfma_f32_16x16x32_bf16 v[0:3], v[180:183], v[212:215], v[0:3]
	s_setprio 0
	s_barrier
	s_add_i32 s41, s41, 2
	s_add_u32 s72, s72, 0x100
	s_addc_u32 s73, s73, 0
	s_add_u32 s39, s39, 0x100
	s_addc_u32 s40, s40, 0
	s_cmp_gt_u32 s41, 61
	s_cbranch_scc0 .LBB0_182
	s_and_b64 vcc, exec, s[6:7]
	s_cbranch_vccz .LBB0_185
	s_barrier

.LBB0_401:
	ds_read_b128 v[142:145], v169
	ds_read_b128 v[146:149], v169 offset:1024
	ds_read_b128 v[150:153], v169 offset:2048
	ds_read_b128 v[154:157], v169 offset:3072
	ds_read_b128 v[158:161], v170
	ds_read_b128 v[162:165], v170 offset:1024
	ds_read_b128 v[172:175], v170 offset:2048
	ds_read_b128 v[176:179], v170 offset:3072
	s_add_i32 s38, s30, 2
	s_add_u32 s46, s44, 0x100
	s_addc_u32 s47, s45, 0
	s_cmp_eq_u32 s17, s30
	s_cselect_b32 s30, s34, s46
	s_cselect_b32 s31, s35, s47
	s_cselect_b32 s53, s41, s37
	s_cselect_b32 s52, s40, s36
	v_lshl_add_u64 v[212:213], s[44:45], 0, v[136:137]
	s_add_i32 m0, s60, 0xc000
	ds_read_b128 v[180:183], v171
	ds_read_b128 v[184:187], v171 offset:1024
	ds_read_b128 v[188:191], v171 offset:2048
	ds_read_b128 v[192:195], v171 offset:3072
	ds_read_b128 v[196:199], v171 offset:4096
	ds_read_b128 v[200:203], v171 offset:5120
	ds_read_b128 v[204:207], v171 offset:6144
	ds_read_b128 v[208:211], v171 offset:7168
	global_load_lds_dwordx4 v[212:213], off
	v_lshl_add_u64 v[212:213], s[44:45], 0, v[138:139]
	s_add_i32 m0, s60, 0xe000
	s_nop 0
	global_load_lds_dwordx4 v[212:213], off
	s_waitcnt vmcnt(8)
	s_waitcnt lgkmcnt(0)
	s_barrier
	s_setprio 1
	v_mfma_f32_16x16x32_bf16 v[124:127], v[142:145], v[180:183], v[124:127]
	v_mfma_f32_16x16x32_bf16 v[120:123], v[150:153], v[180:183], v[120:123]
	v_mfma_f32_16x16x32_bf16 v[108:111], v[142:145], v[188:191], v[108:111]
	v_mfma_f32_16x16x32_bf16 v[104:107], v[150:153], v[188:191], v[104:107]
	v_mfma_f32_16x16x32_bf16 v[92:95], v[142:145], v[196:199], v[92:95]
	v_mfma_f32_16x16x32_bf16 v[88:91], v[150:153], v[196:199], v[88:91]
	v_mfma_f32_16x16x32_bf16 v[76:79], v[142:145], v[204:207], v[76:79]
	v_mfma_f32_16x16x32_bf16 v[72:75], v[150:153], v[204:207], v[72:75]
	v_mfma_f32_16x16x32_bf16 v[124:127], v[146:149], v[184:187], v[124:127]
	v_mfma_f32_16x16x32_bf16 v[120:123], v[154:157], v[184:187], v[120:123]
	v_mfma_f32_16x16x32_bf16 v[108:111], v[146:149], v[192:195], v[108:111]
	v_mfma_f32_16x16x32_bf16 v[104:107], v[154:157], v[192:195], v[104:107]
	v_mfma_f32_16x16x32_bf16 v[92:95], v[146:149], v[200:203], v[92:95]
	v_mfma_f32_16x16x32_bf16 v[88:91], v[154:157], v[200:203], v[88:91]
	v_mfma_f32_16x16x32_bf16 v[76:79], v[146:149], v[208:211], v[76:79]
	v_mfma_f32_16x16x32_bf16 v[72:75], v[154:157], v[208:211], v[72:75]
	v_mfma_f32_16x16x32_bf16 v[116:119], v[158:161], v[180:183], v[116:119]
	v_mfma_f32_16x16x32_bf16 v[112:115], v[172:175], v[180:183], v[112:115]
	v_mfma_f32_16x16x32_bf16 v[100:103], v[158:161], v[188:191], v[100:103]
	v_mfma_f32_16x16x32_bf16 v[96:99], v[172:175], v[188:191], v[96:99]
	v_mfma_f32_16x16x32_bf16 v[84:87], v[158:161], v[196:199], v[84:87]
	v_mfma_f32_16x16x32_bf16 v[80:83], v[172:175], v[196:199], v[80:83]
	v_mfma_f32_16x16x32_bf16 v[68:71], v[158:161], v[204:207], v[68:71]
	v_mfma_f32_16x16x32_bf16 v[64:67], v[172:175], v[204:207], v[64:67]
	v_mfma_f32_16x16x32_bf16 v[116:119], v[162:165], v[184:187], v[116:119]
	v_mfma_f32_16x16x32_bf16 v[112:115], v[176:179], v[184:187], v[112:115]
	v_mfma_f32_16x16x32_bf16 v[100:103], v[162:165], v[192:195], v[100:103]
	v_mfma_f32_16x16x32_bf16 v[96:99], v[176:179], v[192:195], v[96:99]
	v_mfma_f32_16x16x32_bf16 v[84:87], v[162:165], v[200:203], v[84:87]
	v_mfma_f32_16x16x32_bf16 v[80:83], v[176:179], v[200:203], v[80:83]
	v_mfma_f32_16x16x32_bf16 v[68:71], v[162:165], v[208:211], v[68:71]
	v_mfma_f32_16x16x32_bf16 v[64:67], v[176:179], v[208:211], v[64:67]
	s_setprio 0
	s_barrier
	s_add_i32 s39, s76, s33
	v_lshl_add_u64 v[212:213], s[52:53], 0, v[130:131]
	s_mov_b32 m0, s39
	ds_read_b128 v[180:183], v171 offset:16384
	ds_read_b128 v[184:187], v171 offset:17408
	ds_read_b128 v[188:191], v171 offset:18432
	ds_read_b128 v[192:195], v171 offset:19456
	ds_read_b128 v[196:199], v171 offset:20480
	ds_read_b128 v[200:203], v171 offset:21504
	ds_read_b128 v[204:207], v171 offset:22528
	ds_read_b128 v[208:211], v171 offset:23552
	global_load_lds_dwordx4 v[212:213], off
	s_add_i32 m0, s39, 0x2000
	s_add_u32 s42, s52, 0x2b0000
	v_lshl_add_u64 v[214:215], s[52:53], 0, v[134:135]
	s_addc_u32 s43, s53, 0
	s_add_i32 s39, s77, s33
	global_load_lds_dwordx4 v[214:215], off
	v_lshl_add_u64 v[216:217], s[42:43], 0, v[130:131]
	s_mov_b32 m0, s39
	v_lshl_add_u64 v[218:219], s[30:31], 0, v[132:133]
	global_load_lds_dwordx4 v[216:217], off
	v_lshl_add_u64 v[216:217], s[42:43], 0, v[134:135]
	s_add_i32 m0, s39, 0x2000
	s_nop 0
	global_load_lds_dwordx4 v[216:217], off
	v_lshl_add_u64 v[216:217], s[30:31], 0, v[128:129]
	s_mov_b32 m0, s60
	s_nop 0
	global_load_lds_dwordx4 v[216:217], off
	s_mov_b32 m0, s61
	s_nop 0
	global_load_lds_dwordx4 v[218:219], off
	s_waitcnt vmcnt(8)
	s_waitcnt lgkmcnt(0)
	s_barrier
	s_setprio 1
	v_mfma_f32_16x16x32_bf16 v[60:63], v[142:145], v[180:183], v[60:63]
	v_mfma_f32_16x16x32_bf16 v[56:59], v[150:153], v[180:183], v[56:59]
	v_mfma_f32_16x16x32_bf16 v[44:47], v[142:145], v[188:191], v[44:47]
	v_mfma_f32_16x16x32_bf16 v[40:43], v[150:153], v[188:191], v[40:43]
	v_mfma_f32_16x16x32_bf16 v[28:31], v[142:145], v[196:199], v[28:31]
	v_mfma_f32_16x16x32_bf16 v[24:27], v[150:153], v[196:199], v[24:27]
	v_mfma_f32_16x16x32_bf16 v[12:15], v[142:145], v[204:207], v[12:15]
	v_mfma_f32_16x16x32_bf16 v[8:11], v[150:153], v[204:207], v[8:11]
	v_mfma_f32_16x16x32_bf16 v[60:63], v[146:149], v[184:187], v[60:63]
	v_mfma_f32_16x16x32_bf16 v[56:59], v[154:157], v[184:187], v[56:59]
	v_mfma_f32_16x16x32_bf16 v[44:47], v[146:149], v[192:195], v[44:47]
	v_mfma_f32_16x16x32_bf16 v[40:43], v[154:157], v[192:195], v[40:43]
	v_mfma_f32_16x16x32_bf16 v[28:31], v[146:149], v[200:203], v[28:31]
	v_mfma_f32_16x16x32_bf16 v[24:27], v[154:157], v[200:203], v[24:27]
	v_mfma_f32_16x16x32_bf16 v[12:15], v[146:149], v[208:211], v[12:15]
	v_mfma_f32_16x16x32_bf16 v[8:11], v[154:157], v[208:211], v[8:11]
	v_mfma_f32_16x16x32_bf16 v[52:55], v[158:161], v[180:183], v[52:55]
	v_mfma_f32_16x16x32_bf16 v[48:51], v[172:175], v[180:183], v[48:51]
	v_mfma_f32_16x16x32_bf16 v[36:39], v[158:161], v[188:191], v[36:39]
	v_mfma_f32_16x16x32_bf16 v[32:35], v[172:175], v[188:191], v[32:35]
	v_mfma_f32_16x16x32_bf16 v[20:23], v[158:161], v[196:199], v[20:23]
	v_mfma_f32_16x16x32_bf16 v[16:19], v[172:175], v[196:199], v[16:19]
	v_mfma_f32_16x16x32_bf16 v[4:7], v[158:161], v[204:207], v[4:7]
	v_mfma_f32_16x16x32_bf16 v[0:3], v[172:175], v[204:207], v[0:3]
	v_mfma_f32_16x16x32_bf16 v[52:55], v[162:165], v[184:187], v[52:55]
	v_mfma_f32_16x16x32_bf16 v[48:51], v[176:179], v[184:187], v[48:51]
	v_mfma_f32_16x16x32_bf16 v[36:39], v[162:165], v[192:195], v[36:39]
	v_mfma_f32_16x16x32_bf16 v[32:35], v[176:179], v[192:195], v[32:35]
	v_mfma_f32_16x16x32_bf16 v[20:23], v[162:165], v[200:203], v[20:23]
	v_mfma_f32_16x16x32_bf16 v[16:19], v[176:179], v[200:203], v[16:19]
	v_mfma_f32_16x16x32_bf16 v[4:7], v[162:165], v[208:211], v[4:7]
	v_mfma_f32_16x16x32_bf16 v[0:3], v[176:179], v[208:211], v[0:3]
	s_setprio 0
	s_barrier
	s_add_i32 s39, 0, 0x18000
	s_add_i32 s42, 0, 0x1c000
	v_add_u32_e32 v154, s39, v167
	v_add_u32_e32 v176, s42, v167
	ds_read_b128 v[142:145], v154
	ds_read_b128 v[146:149], v154 offset:1024
	ds_read_b128 v[150:153], v154 offset:2048
	ds_read_b128 v[154:157], v154 offset:3072
	ds_read_b128 v[158:161], v176
	ds_read_b128 v[162:165], v176 offset:1024
	ds_read_b128 v[172:175], v176 offset:2048
	ds_read_b128 v[176:179], v176 offset:3072
	s_add_u32 s30, s30, 0x2b0000
	s_addc_u32 s31, s31, 0
	s_mov_b32 m0, s72
	v_lshl_add_u64 v[220:221], s[30:31], 0, v[128:129]
	ds_read_b128 v[180:183], v171 offset:32768
	ds_read_b128 v[184:187], v171 offset:33792
	ds_read_b128 v[188:191], v171 offset:34816
	ds_read_b128 v[192:195], v171 offset:35840
	ds_read_b128 v[196:199], v171 offset:36864
	ds_read_b128 v[200:203], v171 offset:37888
	ds_read_b128 v[204:207], v171 offset:38912
	ds_read_b128 v[208:211], v171 offset:39936
	global_load_lds_dwordx4 v[220:221], off
	v_lshl_add_u64 v[220:221], s[30:31], 0, v[132:133]
	s_mov_b32 m0, s73
	s_nop 0
	global_load_lds_dwordx4 v[220:221], off
	s_waitcnt vmcnt(8)
	s_waitcnt lgkmcnt(0)
	s_barrier
	s_setprio 1
	v_mfma_f32_16x16x32_bf16 v[124:127], v[142:145], v[180:183], v[124:127]
	v_mfma_f32_16x16x32_bf16 v[120:123], v[150:153], v[180:183], v[120:123]
	v_mfma_f32_16x16x32_bf16 v[108:111], v[142:145], v[188:191], v[108:111]
	v_mfma_f32_16x16x32_bf16 v[104:107], v[150:153], v[188:191], v[104:107]
	v_mfma_f32_16x16x32_bf16 v[92:95], v[142:145], v[196:199], v[92:95]
	v_mfma_f32_16x16x32_bf16 v[88:91], v[150:153], v[196:199], v[88:91]
	v_mfma_f32_16x16x32_bf16 v[76:79], v[142:145], v[204:207], v[76:79]
	v_mfma_f32_16x16x32_bf16 v[72:75], v[150:153], v[204:207], v[72:75]
	v_mfma_f32_16x16x32_bf16 v[124:127], v[146:149], v[184:187], v[124:127]
	v_mfma_f32_16x16x32_bf16 v[120:123], v[154:157], v[184:187], v[120:123]
	v_mfma_f32_16x16x32_bf16 v[108:111], v[146:149], v[192:195], v[108:111]
	v_mfma_f32_16x16x32_bf16 v[104:107], v[154:157], v[192:195], v[104:107]
	v_mfma_f32_16x16x32_bf16 v[92:95], v[146:149], v[200:203], v[92:95]
	v_mfma_f32_16x16x32_bf16 v[88:91], v[154:157], v[200:203], v[88:91]
	v_mfma_f32_16x16x32_bf16 v[76:79], v[146:149], v[208:211], v[76:79]
	v_mfma_f32_16x16x32_bf16 v[72:75], v[154:157], v[208:211], v[72:75]
	v_mfma_f32_16x16x32_bf16 v[116:119], v[158:161], v[180:183], v[116:119]
	v_mfma_f32_16x16x32_bf16 v[112:115], v[172:175], v[180:183], v[112:115]
	v_mfma_f32_16x16x32_bf16 v[100:103], v[158:161], v[188:191], v[100:103]
	v_mfma_f32_16x16x32_bf16 v[96:99], v[172:175], v[188:191], v[96:99]
	v_mfma_f32_16x16x32_bf16 v[84:87], v[158:161], v[196:199], v[84:87]
	v_mfma_f32_16x16x32_bf16 v[80:83], v[172:175], v[196:199], v[80:83]
	v_mfma_f32_16x16x32_bf16 v[68:71], v[158:161], v[204:207], v[68:71]
	v_mfma_f32_16x16x32_bf16 v[64:67], v[172:175], v[204:207], v[64:67]
	v_mfma_f32_16x16x32_bf16 v[116:119], v[162:165], v[184:187], v[116:119]
	v_mfma_f32_16x16x32_bf16 v[112:115], v[176:179], v[184:187], v[112:115]
	v_mfma_f32_16x16x32_bf16 v[100:103], v[162:165], v[192:195], v[100:103]
	v_mfma_f32_16x16x32_bf16 v[96:99], v[176:179], v[192:195], v[96:99]
	v_mfma_f32_16x16x32_bf16 v[84:87], v[162:165], v[200:203], v[84:87]
	v_mfma_f32_16x16x32_bf16 v[80:83], v[176:179], v[200:203], v[80:83]
	v_mfma_f32_16x16x32_bf16 v[68:71], v[162:165], v[208:211], v[68:71]
	v_mfma_f32_16x16x32_bf16 v[64:67], v[176:179], v[208:211], v[64:67]
	s_setprio 0
	s_barrier
	s_add_i32 s30, s39, s33
	v_lshl_add_u64 v[212:213], v[212:213], 0, s[10:11]
	s_mov_b32 m0, s30
	ds_read_b128 v[180:183], v171 offset:49152
	ds_read_b128 v[184:187], v171 offset:50176
	ds_read_b128 v[188:191], v171 offset:51200
	ds_read_b128 v[192:195], v171 offset:52224
	ds_read_b128 v[196:199], v171 offset:53248
	ds_read_b128 v[200:203], v171 offset:54272
	ds_read_b128 v[204:207], v171 offset:55296
	ds_read_b128 v[208:211], v171 offset:56320
	global_load_lds_dwordx4 v[212:213], off
	s_add_i32 m0, s30, 0x2000
	s_add_u32 s30, s52, 0x2b0080
	v_lshl_add_u64 v[212:213], v[214:215], 0, s[10:11]
	s_addc_u32 s31, s53, 0
	s_add_i32 s39, s42, s33
	global_load_lds_dwordx4 v[212:213], off
	v_lshl_add_u64 v[212:213], s[30:31], 0, v[130:131]
	s_mov_b32 m0, s39
	s_nop 0
	global_load_lds_dwordx4 v[212:213], off
	v_lshl_add_u64 v[212:213], s[30:31], 0, v[134:135]
	s_add_i32 m0, s39, 0x2000
	s_nop 0
	global_load_lds_dwordx4 v[212:213], off
	v_lshl_add_u64 v[212:213], v[216:217], 0, s[10:11]
	s_mov_b32 m0, s28
	s_nop 0
	global_load_lds_dwordx4 v[212:213], off
	v_lshl_add_u64 v[212:213], v[218:219], 0, s[10:11]
	s_mov_b32 m0, s29
	s_nop 0
	global_load_lds_dwordx4 v[212:213], off
	s_waitcnt vmcnt(8)
	s_waitcnt lgkmcnt(0)
	s_barrier
	s_setprio 1
	v_mfma_f32_16x16x32_bf16 v[60:63], v[142:145], v[180:183], v[60:63]
	v_mfma_f32_16x16x32_bf16 v[56:59], v[150:153], v[180:183], v[56:59]
	v_mfma_f32_16x16x32_bf16 v[44:47], v[142:145], v[188:191], v[44:47]
	v_mfma_f32_16x16x32_bf16 v[40:43], v[150:153], v[188:191], v[40:43]
	v_mfma_f32_16x16x32_bf16 v[28:31], v[142:145], v[196:199], v[28:31]
	v_mfma_f32_16x16x32_bf16 v[24:27], v[150:153], v[196:199], v[24:27]
	v_mfma_f32_16x16x32_bf16 v[12:15], v[142:145], v[204:207], v[12:15]
	v_mfma_f32_16x16x32_bf16 v[8:11], v[150:153], v[204:207], v[8:11]
	v_mfma_f32_16x16x32_bf16 v[60:63], v[146:149], v[184:187], v[60:63]
	v_mfma_f32_16x16x32_bf16 v[56:59], v[154:157], v[184:187], v[56:59]
	v_mfma_f32_16x16x32_bf16 v[44:47], v[146:149], v[192:195], v[44:47]
	v_mfma_f32_16x16x32_bf16 v[40:43], v[154:157], v[192:195], v[40:43]
	v_mfma_f32_16x16x32_bf16 v[28:31], v[146:149], v[200:203], v[28:31]
	v_mfma_f32_16x16x32_bf16 v[24:27], v[154:157], v[200:203], v[24:27]
	v_mfma_f32_16x16x32_bf16 v[12:15], v[146:149], v[208:211], v[12:15]
	v_mfma_f32_16x16x32_bf16 v[8:11], v[154:157], v[208:211], v[8:11]
	v_mfma_f32_16x16x32_bf16 v[52:55], v[158:161], v[180:183], v[52:55]
	v_mfma_f32_16x16x32_bf16 v[48:51], v[172:175], v[180:183], v[48:51]
	v_mfma_f32_16x16x32_bf16 v[36:39], v[158:161], v[188:191], v[36:39]
	v_mfma_f32_16x16x32_bf16 v[32:35], v[172:175], v[188:191], v[32:35]
	v_mfma_f32_16x16x32_bf16 v[20:23], v[158:161], v[196:199], v[20:23]
	v_mfma_f32_16x16x32_bf16 v[16:19], v[172:175], v[196:199], v[16:19]
	v_mfma_f32_16x16x32_bf16 v[4:7], v[158:161], v[204:207], v[4:7]
	v_mfma_f32_16x16x32_bf16 v[0:3], v[172:175], v[204:207], v[0:3]
	v_mfma_f32_16x16x32_bf16 v[52:55], v[162:165], v[184:187], v[52:55]
	v_mfma_f32_16x16x32_bf16 v[48:51], v[176:179], v[184:187], v[48:51]
	v_mfma_f32_16x16x32_bf16 v[36:39], v[162:165], v[192:195], v[36:39]
	v_mfma_f32_16x16x32_bf16 v[32:35], v[176:179], v[192:195], v[32:35]
	v_mfma_f32_16x16x32_bf16 v[20:23], v[162:165], v[200:203], v[20:23]
	v_mfma_f32_16x16x32_bf16 v[16:19], v[176:179], v[200:203], v[16:19]
	v_mfma_f32_16x16x32_bf16 v[4:7], v[162:165], v[208:211], v[4:7]
	v_mfma_f32_16x16x32_bf16 v[0:3], v[176:179], v[208:211], v[0:3]
	s_setprio 0
	s_barrier
	s_add_u32 s36, s36, 0x100
	s_addc_u32 s37, s37, 0
	s_cmp_ge_i32 s38, s87
	s_mov_b64 s[44:45], s[46:47]
	s_mov_b32 s30, s38
	s_cbranch_scc0 .LBB0_401
	s_and_b64 vcc, exec, s[12:13]
	s_cbranch_vccz .LBB0_404

.LBB0_576:
	ds_read_b128 v[154:157], v149
	ds_read_b128 v[158:161], v149 offset:1024
	ds_read_b128 v[162:165], v149 offset:2048
	ds_read_b128 v[166:169], v149 offset:3072
	ds_read_b128 v[170:173], v150
	ds_read_b128 v[174:177], v150 offset:1024
	ds_read_b128 v[178:181], v150 offset:2048
	ds_read_b128 v[182:185], v150 offset:3072
	s_add_i32 s42, s30, 2
	s_add_u32 s43, s52, 0xfff00080
	s_addc_u32 s31, s53, -1
	s_cmp_eq_u32 s37, s30
	s_cselect_b32 s30, s15, s43
	s_cselect_b32 s31, s7, s31
	s_cselect_b32 s55, s17, s39
	s_cselect_b32 s54, s35, s38
	v_lshl_add_u64 v[144:145], s[52:53], 0, v[138:139]
	s_add_i32 m0, s9, 0xc000
	ds_read_b128 v[186:189], v151
	ds_read_b128 v[190:193], v151 offset:1024
	ds_read_b128 v[194:197], v151 offset:2048
	ds_read_b128 v[198:201], v151 offset:3072
	ds_read_b128 v[202:205], v151 offset:4096
	ds_read_b128 v[206:209], v151 offset:5120
	ds_read_b128 v[210:213], v151 offset:6144
	ds_read_b128 v[214:217], v151 offset:7168
	global_load_lds_dwordx4 v[144:145], off
	v_lshl_add_u64 v[144:145], s[52:53], 0, v[140:141]
	s_add_i32 m0, s9, 0xe000
	s_nop 0
	global_load_lds_dwordx4 v[144:145], off
	s_waitcnt vmcnt(8)
	s_waitcnt lgkmcnt(0)
	s_barrier
	s_setprio 1
	v_mfma_f32_16x16x32_bf16 v[60:63], v[154:157], v[186:189], v[60:63]
	v_mfma_f32_16x16x32_bf16 v[56:59], v[162:165], v[186:189], v[56:59]
	v_mfma_f32_16x16x32_bf16 v[52:55], v[154:157], v[194:197], v[52:55]
	v_mfma_f32_16x16x32_bf16 v[48:51], v[162:165], v[194:197], v[48:51]
	v_mfma_f32_16x16x32_bf16 v[44:47], v[154:157], v[202:205], v[44:47]
	v_mfma_f32_16x16x32_bf16 v[40:43], v[162:165], v[202:205], v[40:43]
	v_mfma_f32_16x16x32_bf16 v[36:39], v[154:157], v[210:213], v[36:39]
	v_mfma_f32_16x16x32_bf16 v[32:35], v[162:165], v[210:213], v[32:35]
	v_mfma_f32_16x16x32_bf16 v[60:63], v[158:161], v[190:193], v[60:63]
	v_mfma_f32_16x16x32_bf16 v[56:59], v[166:169], v[190:193], v[56:59]
	v_mfma_f32_16x16x32_bf16 v[52:55], v[158:161], v[198:201], v[52:55]
	v_mfma_f32_16x16x32_bf16 v[48:51], v[166:169], v[198:201], v[48:51]
	v_mfma_f32_16x16x32_bf16 v[44:47], v[158:161], v[206:209], v[44:47]
	v_mfma_f32_16x16x32_bf16 v[40:43], v[166:169], v[206:209], v[40:43]
	v_mfma_f32_16x16x32_bf16 v[36:39], v[158:161], v[214:217], v[36:39]
	v_mfma_f32_16x16x32_bf16 v[32:35], v[166:169], v[214:217], v[32:35]
	v_mfma_f32_16x16x32_bf16 v[124:127], v[170:173], v[186:189], v[124:127]
	v_mfma_f32_16x16x32_bf16 v[120:123], v[178:181], v[186:189], v[120:123]
	v_mfma_f32_16x16x32_bf16 v[116:119], v[170:173], v[194:197], v[116:119]
	v_mfma_f32_16x16x32_bf16 v[112:115], v[178:181], v[194:197], v[112:115]
	v_mfma_f32_16x16x32_bf16 v[108:111], v[170:173], v[202:205], v[108:111]
	v_mfma_f32_16x16x32_bf16 v[104:107], v[178:181], v[202:205], v[104:107]
	v_mfma_f32_16x16x32_bf16 v[100:103], v[170:173], v[210:213], v[100:103]
	v_mfma_f32_16x16x32_bf16 v[96:99], v[178:181], v[210:213], v[96:99]
	v_mfma_f32_16x16x32_bf16 v[124:127], v[174:177], v[190:193], v[124:127]
	v_mfma_f32_16x16x32_bf16 v[120:123], v[182:185], v[190:193], v[120:123]
	v_mfma_f32_16x16x32_bf16 v[116:119], v[174:177], v[198:201], v[116:119]
	v_mfma_f32_16x16x32_bf16 v[112:115], v[182:185], v[198:201], v[112:115]
	v_mfma_f32_16x16x32_bf16 v[108:111], v[174:177], v[206:209], v[108:111]
	v_mfma_f32_16x16x32_bf16 v[104:107], v[182:185], v[206:209], v[104:107]
	v_mfma_f32_16x16x32_bf16 v[100:103], v[174:177], v[214:217], v[100:103]
	v_mfma_f32_16x16x32_bf16 v[96:99], v[182:185], v[214:217], v[96:99]
	s_setprio 0
	s_barrier
	s_add_i32 s43, s74, s33
	v_lshl_add_u64 v[144:145], s[54:55], 0, v[130:131]
	s_mov_b32 m0, s43
	ds_read_b128 v[186:189], v151 offset:16384
	ds_read_b128 v[190:193], v151 offset:17408
	ds_read_b128 v[194:197], v151 offset:18432
	ds_read_b128 v[198:201], v151 offset:19456
	ds_read_b128 v[202:205], v151 offset:20480
	ds_read_b128 v[206:209], v151 offset:21504
	ds_read_b128 v[210:213], v151 offset:22528
	ds_read_b128 v[214:217], v151 offset:23552
	global_load_lds_dwordx4 v[144:145], off
	s_add_i32 m0, s43, 0x2000
	s_add_u32 s48, s54, 0x100000
	v_lshl_add_u64 v[218:219], s[54:55], 0, v[134:135]
	s_addc_u32 s49, s55, 0
	s_add_i32 s43, s75, s33
	global_load_lds_dwordx4 v[218:219], off
	v_lshl_add_u64 v[220:221], s[48:49], 0, v[130:131]
	s_mov_b32 m0, s43
	v_lshl_add_u64 v[222:223], s[30:31], 0, v[132:133]
	global_load_lds_dwordx4 v[220:221], off
	v_lshl_add_u64 v[220:221], s[48:49], 0, v[134:135]
	s_add_i32 m0, s43, 0x2000
	s_nop 0
	global_load_lds_dwordx4 v[220:221], off
	v_lshl_add_u64 v[220:221], s[30:31], 0, v[128:129]
	s_mov_b32 m0, s9
	s_nop 0
	global_load_lds_dwordx4 v[220:221], off
	s_mov_b32 m0, s58
	s_nop 0
	global_load_lds_dwordx4 v[222:223], off
	s_waitcnt vmcnt(8)
	s_waitcnt lgkmcnt(0)
	s_barrier
	s_setprio 1
	v_mfma_f32_16x16x32_bf16 v[28:31], v[154:157], v[186:189], v[28:31]
	v_mfma_f32_16x16x32_bf16 v[24:27], v[162:165], v[186:189], v[24:27]
	v_mfma_f32_16x16x32_bf16 v[20:23], v[154:157], v[194:197], v[20:23]
	v_mfma_f32_16x16x32_bf16 v[16:19], v[162:165], v[194:197], v[16:19]
	v_mfma_f32_16x16x32_bf16 v[12:15], v[154:157], v[202:205], v[12:15]
	v_mfma_f32_16x16x32_bf16 v[8:11], v[162:165], v[202:205], v[8:11]
	v_mfma_f32_16x16x32_bf16 v[4:7], v[154:157], v[210:213], v[4:7]
	v_mfma_f32_16x16x32_bf16 v[0:3], v[162:165], v[210:213], v[0:3]
	v_mfma_f32_16x16x32_bf16 v[28:31], v[158:161], v[190:193], v[28:31]
	v_mfma_f32_16x16x32_bf16 v[24:27], v[166:169], v[190:193], v[24:27]
	v_mfma_f32_16x16x32_bf16 v[20:23], v[158:161], v[198:201], v[20:23]
	v_mfma_f32_16x16x32_bf16 v[16:19], v[166:169], v[198:201], v[16:19]
	v_mfma_f32_16x16x32_bf16 v[12:15], v[158:161], v[206:209], v[12:15]
	v_mfma_f32_16x16x32_bf16 v[8:11], v[166:169], v[206:209], v[8:11]
	v_mfma_f32_16x16x32_bf16 v[4:7], v[158:161], v[214:217], v[4:7]
	v_mfma_f32_16x16x32_bf16 v[0:3], v[166:169], v[214:217], v[0:3]
	v_mfma_f32_16x16x32_bf16 v[92:95], v[170:173], v[186:189], v[92:95]
	v_mfma_f32_16x16x32_bf16 v[88:91], v[178:181], v[186:189], v[88:91]
	v_mfma_f32_16x16x32_bf16 v[84:87], v[170:173], v[194:197], v[84:87]
	v_mfma_f32_16x16x32_bf16 v[80:83], v[178:181], v[194:197], v[80:83]
	v_mfma_f32_16x16x32_bf16 v[76:79], v[170:173], v[202:205], v[76:79]
	v_mfma_f32_16x16x32_bf16 v[72:75], v[178:181], v[202:205], v[72:75]
	v_mfma_f32_16x16x32_bf16 v[68:71], v[170:173], v[210:213], v[68:71]
	v_mfma_f32_16x16x32_bf16 v[64:67], v[178:181], v[210:213], v[64:67]
	v_mfma_f32_16x16x32_bf16 v[92:95], v[174:177], v[190:193], v[92:95]
	v_mfma_f32_16x16x32_bf16 v[88:91], v[182:185], v[190:193], v[88:91]
	v_mfma_f32_16x16x32_bf16 v[84:87], v[174:177], v[198:201], v[84:87]
	v_mfma_f32_16x16x32_bf16 v[80:83], v[182:185], v[198:201], v[80:83]
	v_mfma_f32_16x16x32_bf16 v[76:79], v[174:177], v[206:209], v[76:79]
	v_mfma_f32_16x16x32_bf16 v[72:75], v[182:185], v[206:209], v[72:75]
	v_mfma_f32_16x16x32_bf16 v[68:71], v[174:177], v[214:217], v[68:71]
	v_mfma_f32_16x16x32_bf16 v[64:67], v[182:185], v[214:217], v[64:67]
	s_setprio 0
	s_barrier
	s_add_i32 s43, 0, 0x18000
	v_add_u32_e32 v153, s43, v147
	s_add_i32 s48, 0, 0x1c000
	ds_read_b128 v[154:157], v153
	ds_read_b128 v[158:161], v153 offset:1024
	ds_read_b128 v[162:165], v153 offset:2048
	ds_read_b128 v[166:169], v153 offset:3072
	v_add_u32_e32 v153, s48, v147
	ds_read_b128 v[170:173], v153
	ds_read_b128 v[174:177], v153 offset:1024
	ds_read_b128 v[178:181], v153 offset:2048
	ds_read_b128 v[182:185], v153 offset:3072
	s_add_u32 s30, s30, 0x100000
	s_addc_u32 s31, s31, 0
	s_mov_b32 m0, s59
	v_lshl_add_u64 v[224:225], s[30:31], 0, v[128:129]
	ds_read_b128 v[186:189], v151 offset:32768
	ds_read_b128 v[190:193], v151 offset:33792
	ds_read_b128 v[194:197], v151 offset:34816
	ds_read_b128 v[198:201], v151 offset:35840
	ds_read_b128 v[202:205], v151 offset:36864
	ds_read_b128 v[206:209], v151 offset:37888
	ds_read_b128 v[210:213], v151 offset:38912
	ds_read_b128 v[214:217], v151 offset:39936
	global_load_lds_dwordx4 v[224:225], off
	v_lshl_add_u64 v[224:225], s[30:31], 0, v[132:133]
	s_mov_b32 m0, s60
	s_nop 0
	global_load_lds_dwordx4 v[224:225], off
	s_waitcnt vmcnt(8)
	s_waitcnt lgkmcnt(0)
	s_barrier
	s_setprio 1
	v_mfma_f32_16x16x32_bf16 v[60:63], v[154:157], v[186:189], v[60:63]
	v_mfma_f32_16x16x32_bf16 v[56:59], v[162:165], v[186:189], v[56:59]
	v_mfma_f32_16x16x32_bf16 v[52:55], v[154:157], v[194:197], v[52:55]
	v_mfma_f32_16x16x32_bf16 v[48:51], v[162:165], v[194:197], v[48:51]
	v_mfma_f32_16x16x32_bf16 v[44:47], v[154:157], v[202:205], v[44:47]
	v_mfma_f32_16x16x32_bf16 v[40:43], v[162:165], v[202:205], v[40:43]
	v_mfma_f32_16x16x32_bf16 v[36:39], v[154:157], v[210:213], v[36:39]
	v_mfma_f32_16x16x32_bf16 v[32:35], v[162:165], v[210:213], v[32:35]
	v_mfma_f32_16x16x32_bf16 v[60:63], v[158:161], v[190:193], v[60:63]
	v_mfma_f32_16x16x32_bf16 v[56:59], v[166:169], v[190:193], v[56:59]
	v_mfma_f32_16x16x32_bf16 v[52:55], v[158:161], v[198:201], v[52:55]
	v_mfma_f32_16x16x32_bf16 v[48:51], v[166:169], v[198:201], v[48:51]
	v_mfma_f32_16x16x32_bf16 v[44:47], v[158:161], v[206:209], v[44:47]
	v_mfma_f32_16x16x32_bf16 v[40:43], v[166:169], v[206:209], v[40:43]
	v_mfma_f32_16x16x32_bf16 v[36:39], v[158:161], v[214:217], v[36:39]
	v_mfma_f32_16x16x32_bf16 v[32:35], v[166:169], v[214:217], v[32:35]
	v_mfma_f32_16x16x32_bf16 v[124:127], v[170:173], v[186:189], v[124:127]
	v_mfma_f32_16x16x32_bf16 v[120:123], v[178:181], v[186:189], v[120:123]
	v_mfma_f32_16x16x32_bf16 v[116:119], v[170:173], v[194:197], v[116:119]
	v_mfma_f32_16x16x32_bf16 v[112:115], v[178:181], v[194:197], v[112:115]
	v_mfma_f32_16x16x32_bf16 v[108:111], v[170:173], v[202:205], v[108:111]
	v_mfma_f32_16x16x32_bf16 v[104:107], v[178:181], v[202:205], v[104:107]
	v_mfma_f32_16x16x32_bf16 v[100:103], v[170:173], v[210:213], v[100:103]
	v_mfma_f32_16x16x32_bf16 v[96:99], v[178:181], v[210:213], v[96:99]
	v_mfma_f32_16x16x32_bf16 v[124:127], v[174:177], v[190:193], v[124:127]
	v_mfma_f32_16x16x32_bf16 v[120:123], v[182:185], v[190:193], v[120:123]
	v_mfma_f32_16x16x32_bf16 v[116:119], v[174:177], v[198:201], v[116:119]
	v_mfma_f32_16x16x32_bf16 v[112:115], v[182:185], v[198:201], v[112:115]
	v_mfma_f32_16x16x32_bf16 v[108:111], v[174:177], v[206:209], v[108:111]
	v_mfma_f32_16x16x32_bf16 v[104:107], v[182:185], v[206:209], v[104:107]
	v_mfma_f32_16x16x32_bf16 v[100:103], v[174:177], v[214:217], v[100:103]
	v_mfma_f32_16x16x32_bf16 v[96:99], v[182:185], v[214:217], v[96:99]
	s_setprio 0
	s_barrier
	s_add_i32 s30, s43, s33
	v_lshl_add_u64 v[144:145], v[144:145], 0, s[4:5]
	s_mov_b32 m0, s30
	ds_read_b128 v[186:189], v151 offset:49152
	ds_read_b128 v[190:193], v151 offset:50176
	ds_read_b128 v[194:197], v151 offset:51200
	ds_read_b128 v[198:201], v151 offset:52224
	ds_read_b128 v[202:205], v151 offset:53248
	ds_read_b128 v[206:209], v151 offset:54272
	ds_read_b128 v[210:213], v151 offset:55296
	ds_read_b128 v[214:217], v151 offset:56320
	global_load_lds_dwordx4 v[144:145], off
	s_add_i32 m0, s30, 0x2000
	s_add_u32 s30, s54, 0x100080
	v_lshl_add_u64 v[144:145], v[218:219], 0, s[4:5]
	s_addc_u32 s31, s55, 0
	s_add_i32 s43, s48, s33
	global_load_lds_dwordx4 v[144:145], off
	v_lshl_add_u64 v[144:145], s[30:31], 0, v[130:131]
	s_mov_b32 m0, s43
	s_nop 0
	global_load_lds_dwordx4 v[144:145], off
	v_lshl_add_u64 v[144:145], s[30:31], 0, v[134:135]
	s_add_i32 m0, s43, 0x2000
	s_nop 0
	global_load_lds_dwordx4 v[144:145], off
	v_lshl_add_u64 v[144:145], v[220:221], 0, s[4:5]
	s_mov_b32 m0, s70
	s_nop 0
	global_load_lds_dwordx4 v[144:145], off
	v_lshl_add_u64 v[144:145], v[222:223], 0, s[4:5]
	s_mov_b32 m0, s71
	s_nop 0
	global_load_lds_dwordx4 v[144:145], off
	s_waitcnt vmcnt(8)
	s_waitcnt lgkmcnt(0)
	s_barrier
	s_setprio 1
	v_mfma_f32_16x16x32_bf16 v[28:31], v[154:157], v[186:189], v[28:31]
	v_mfma_f32_16x16x32_bf16 v[24:27], v[162:165], v[186:189], v[24:27]
	v_mfma_f32_16x16x32_bf16 v[20:23], v[154:157], v[194:197], v[20:23]
	v_mfma_f32_16x16x32_bf16 v[16:19], v[162:165], v[194:197], v[16:19]
	v_mfma_f32_16x16x32_bf16 v[12:15], v[154:157], v[202:205], v[12:15]
	v_mfma_f32_16x16x32_bf16 v[8:11], v[162:165], v[202:205], v[8:11]
	v_mfma_f32_16x16x32_bf16 v[4:7], v[154:157], v[210:213], v[4:7]
	v_mfma_f32_16x16x32_bf16 v[0:3], v[162:165], v[210:213], v[0:3]
	v_mfma_f32_16x16x32_bf16 v[28:31], v[158:161], v[190:193], v[28:31]
	v_mfma_f32_16x16x32_bf16 v[24:27], v[166:169], v[190:193], v[24:27]
	v_mfma_f32_16x16x32_bf16 v[20:23], v[158:161], v[198:201], v[20:23]
	v_mfma_f32_16x16x32_bf16 v[16:19], v[166:169], v[198:201], v[16:19]
	v_mfma_f32_16x16x32_bf16 v[12:15], v[158:161], v[206:209], v[12:15]
	v_mfma_f32_16x16x32_bf16 v[8:11], v[166:169], v[206:209], v[8:11]
	v_mfma_f32_16x16x32_bf16 v[4:7], v[158:161], v[214:217], v[4:7]
	v_mfma_f32_16x16x32_bf16 v[0:3], v[166:169], v[214:217], v[0:3]
	v_mfma_f32_16x16x32_bf16 v[92:95], v[170:173], v[186:189], v[92:95]
	v_mfma_f32_16x16x32_bf16 v[88:91], v[178:181], v[186:189], v[88:91]
	v_mfma_f32_16x16x32_bf16 v[84:87], v[170:173], v[194:197], v[84:87]
	v_mfma_f32_16x16x32_bf16 v[80:83], v[178:181], v[194:197], v[80:83]
	v_mfma_f32_16x16x32_bf16 v[76:79], v[170:173], v[202:205], v[76:79]
	v_mfma_f32_16x16x32_bf16 v[72:75], v[178:181], v[202:205], v[72:75]
	v_mfma_f32_16x16x32_bf16 v[68:71], v[170:173], v[210:213], v[68:71]
	v_mfma_f32_16x16x32_bf16 v[64:67], v[178:181], v[210:213], v[64:67]
	v_mfma_f32_16x16x32_bf16 v[92:95], v[174:177], v[190:193], v[92:95]
	v_mfma_f32_16x16x32_bf16 v[88:91], v[182:185], v[190:193], v[88:91]
	v_mfma_f32_16x16x32_bf16 v[84:87], v[174:177], v[198:201], v[84:87]
	v_mfma_f32_16x16x32_bf16 v[80:83], v[182:185], v[198:201], v[80:83]
	v_mfma_f32_16x16x32_bf16 v[76:79], v[174:177], v[206:209], v[76:79]
	v_mfma_f32_16x16x32_bf16 v[72:75], v[182:185], v[206:209], v[72:75]
	v_mfma_f32_16x16x32_bf16 v[68:71], v[174:177], v[214:217], v[68:71]
	v_mfma_f32_16x16x32_bf16 v[64:67], v[182:185], v[214:217], v[64:67]
	s_setprio 0
	s_barrier
	s_add_u32 s52, s52, 0x100
	s_addc_u32 s53, s53, 0
	s_add_u32 s38, s38, 0x100
	s_addc_u32 s39, s39, 0
	s_cmp_ge_i32 s42, s36
	s_mov_b32 s30, s42
	s_cbranch_scc0 .LBB0_576
	s_and_b64 vcc, exec, s[10:11]
	s_cbranch_vccz .LBB0_581

.LBB0_738:
	ds_read_b128 v[182:185], v129
	ds_read_b128 v[186:189], v129 offset:1024
	ds_read_b128 v[190:193], v129 offset:2048
	ds_read_b128 v[194:197], v129 offset:3072
	ds_read_b128 v[198:201], v178
	ds_read_b128 v[202:205], v178 offset:1024
	ds_read_b128 v[206:209], v178 offset:2048
	ds_read_b128 v[210:213], v178 offset:3072
	s_add_u32 s30, s44, 0xfffc0080
	s_addc_u32 s31, s45, -1
	s_cmp_eq_u32 s50, 12
	s_cselect_b32 s31, s36, s31
	s_cselect_b32 s30, s37, s30
	s_cselect_b32 s47, s35, s49
	s_cselect_b32 s46, s39, s48
	v_lshl_add_u64 v[154:155], s[44:45], 0, v[146:147]
	s_add_i32 m0, s54, 0xc000
	ds_read_b128 v[214:217], v179
	ds_read_b128 v[218:221], v179 offset:1024
	ds_read_b128 v[222:225], v179 offset:2048
	ds_read_b128 v[226:229], v179 offset:3072
	ds_read_b128 v[230:233], v179 offset:4096
	ds_read_b128 v[234:237], v179 offset:5120
	ds_read_b128 v[238:241], v179 offset:6144
	ds_read_b128 v[242:245], v179 offset:7168
	global_load_lds_dwordx4 v[154:155], off
	v_lshl_add_u64 v[154:155], s[44:45], 0, v[148:149]
	s_add_i32 m0, s54, 0xe000
	s_nop 0
	global_load_lds_dwordx4 v[154:155], off
	s_waitcnt vmcnt(8)
	s_waitcnt lgkmcnt(0)
	s_barrier
	s_setprio 1
	v_mfma_f32_16x16x32_bf16 v[124:127], v[182:185], v[214:217], v[124:127]
	v_mfma_f32_16x16x32_bf16 v[120:123], v[190:193], v[214:217], v[120:123]
	v_mfma_f32_16x16x32_bf16 v[116:119], v[182:185], v[222:225], v[116:119]
	v_mfma_f32_16x16x32_bf16 v[108:111], v[190:193], v[222:225], v[108:111]
	v_mfma_f32_16x16x32_bf16 v[100:103], v[182:185], v[230:233], v[100:103]
	v_mfma_f32_16x16x32_bf16 v[92:95], v[190:193], v[230:233], v[92:95]
	v_mfma_f32_16x16x32_bf16 v[84:87], v[182:185], v[238:241], v[84:87]
	v_mfma_f32_16x16x32_bf16 v[76:79], v[190:193], v[238:241], v[76:79]
	v_mfma_f32_16x16x32_bf16 v[124:127], v[186:189], v[218:221], v[124:127]
	v_mfma_f32_16x16x32_bf16 v[120:123], v[194:197], v[218:221], v[120:123]
	v_mfma_f32_16x16x32_bf16 v[116:119], v[186:189], v[226:229], v[116:119]
	v_mfma_f32_16x16x32_bf16 v[108:111], v[194:197], v[226:229], v[108:111]
	v_mfma_f32_16x16x32_bf16 v[100:103], v[186:189], v[234:237], v[100:103]
	v_mfma_f32_16x16x32_bf16 v[92:95], v[194:197], v[234:237], v[92:95]
	v_mfma_f32_16x16x32_bf16 v[84:87], v[186:189], v[242:245], v[84:87]
	v_mfma_f32_16x16x32_bf16 v[76:79], v[194:197], v[242:245], v[76:79]
	v_mfma_f32_16x16x32_bf16 v[112:115], v[198:201], v[214:217], v[112:115]
	v_mfma_f32_16x16x32_bf16 v[104:107], v[206:209], v[214:217], v[104:107]
	v_mfma_f32_16x16x32_bf16 v[96:99], v[198:201], v[222:225], v[96:99]
	v_mfma_f32_16x16x32_bf16 v[88:91], v[206:209], v[222:225], v[88:91]
	v_mfma_f32_16x16x32_bf16 v[80:83], v[198:201], v[230:233], v[80:83]
	v_mfma_f32_16x16x32_bf16 v[72:75], v[206:209], v[230:233], v[72:75]
	v_mfma_f32_16x16x32_bf16 v[68:71], v[198:201], v[238:241], v[68:71]
	v_mfma_f32_16x16x32_bf16 v[64:67], v[206:209], v[238:241], v[64:67]
	v_mfma_f32_16x16x32_bf16 v[112:115], v[202:205], v[218:221], v[112:115]
	v_mfma_f32_16x16x32_bf16 v[104:107], v[210:213], v[218:221], v[104:107]
	v_mfma_f32_16x16x32_bf16 v[96:99], v[202:205], v[226:229], v[96:99]
	v_mfma_f32_16x16x32_bf16 v[88:91], v[210:213], v[226:229], v[88:91]
	v_mfma_f32_16x16x32_bf16 v[80:83], v[202:205], v[234:237], v[80:83]
	v_mfma_f32_16x16x32_bf16 v[72:75], v[210:213], v[234:237], v[72:75]
	v_mfma_f32_16x16x32_bf16 v[68:71], v[202:205], v[242:245], v[68:71]
	v_mfma_f32_16x16x32_bf16 v[64:67], v[210:213], v[242:245], v[64:67]
	s_setprio 0
	s_barrier
	s_add_i32 s51, s62, s15
	v_lshl_add_u64 v[154:155], s[46:47], 0, v[136:137]
	s_mov_b32 m0, s51
	ds_read_b128 v[214:217], v179 offset:16384
	ds_read_b128 v[218:221], v179 offset:17408
	ds_read_b128 v[222:225], v179 offset:18432
	ds_read_b128 v[226:229], v179 offset:19456
	ds_read_b128 v[230:233], v179 offset:20480
	ds_read_b128 v[234:237], v179 offset:21504
	ds_read_b128 v[238:241], v179 offset:22528
	ds_read_b128 v[242:245], v179 offset:23552
	global_load_lds_dwordx4 v[154:155], off
	s_add_i32 m0, s51, 0x2000
	s_add_u32 s70, s46, 0x40000
	v_lshl_add_u64 v[246:247], s[46:47], 0, v[132:133]
	s_addc_u32 s71, s47, 0
	s_add_i32 s51, s63, s15
	global_load_lds_dwordx4 v[246:247], off
	v_lshl_add_u64 v[248:249], s[70:71], 0, v[136:137]
	s_mov_b32 m0, s51
	v_lshl_add_u64 v[250:251], s[30:31], 0, v[134:135]
	global_load_lds_dwordx4 v[248:249], off
	v_lshl_add_u64 v[248:249], s[70:71], 0, v[132:133]
	s_add_i32 m0, s51, 0x2000
	s_nop 0
	global_load_lds_dwordx4 v[248:249], off
	v_lshl_add_u64 v[248:249], s[30:31], 0, v[138:139]
	s_mov_b32 m0, s54
	s_nop 0
	global_load_lds_dwordx4 v[248:249], off
	s_mov_b32 m0, s55
	s_nop 0
	global_load_lds_dwordx4 v[250:251], off
	s_waitcnt vmcnt(8)
	s_waitcnt lgkmcnt(0)
	s_barrier
	s_setprio 1
	v_mfma_f32_16x16x32_bf16 v[60:63], v[182:185], v[214:217], v[60:63]
	v_mfma_f32_16x16x32_bf16 v[56:59], v[190:193], v[214:217], v[56:59]
	v_mfma_f32_16x16x32_bf16 v[52:55], v[182:185], v[222:225], v[52:55]
	v_mfma_f32_16x16x32_bf16 v[44:47], v[190:193], v[222:225], v[44:47]
	v_mfma_f32_16x16x32_bf16 v[36:39], v[182:185], v[230:233], v[36:39]
	v_mfma_f32_16x16x32_bf16 v[28:31], v[190:193], v[230:233], v[28:31]
	v_mfma_f32_16x16x32_bf16 v[20:23], v[182:185], v[238:241], v[20:23]
	v_mfma_f32_16x16x32_bf16 v[12:15], v[190:193], v[238:241], v[12:15]
	v_mfma_f32_16x16x32_bf16 v[60:63], v[186:189], v[218:221], v[60:63]
	v_mfma_f32_16x16x32_bf16 v[56:59], v[194:197], v[218:221], v[56:59]
	v_mfma_f32_16x16x32_bf16 v[52:55], v[186:189], v[226:229], v[52:55]
	v_mfma_f32_16x16x32_bf16 v[44:47], v[194:197], v[226:229], v[44:47]
	v_mfma_f32_16x16x32_bf16 v[36:39], v[186:189], v[234:237], v[36:39]
	v_mfma_f32_16x16x32_bf16 v[28:31], v[194:197], v[234:237], v[28:31]
	v_mfma_f32_16x16x32_bf16 v[20:23], v[186:189], v[242:245], v[20:23]
	v_mfma_f32_16x16x32_bf16 v[12:15], v[194:197], v[242:245], v[12:15]
	v_mfma_f32_16x16x32_bf16 v[48:51], v[198:201], v[214:217], v[48:51]
	v_mfma_f32_16x16x32_bf16 v[40:43], v[206:209], v[214:217], v[40:43]
	v_mfma_f32_16x16x32_bf16 v[32:35], v[198:201], v[222:225], v[32:35]
	v_mfma_f32_16x16x32_bf16 v[24:27], v[206:209], v[222:225], v[24:27]
	v_mfma_f32_16x16x32_bf16 v[16:19], v[198:201], v[230:233], v[16:19]
	v_mfma_f32_16x16x32_bf16 v[8:11], v[206:209], v[230:233], v[8:11]
	v_mfma_f32_16x16x32_bf16 v[4:7], v[198:201], v[238:241], v[4:7]
	v_mfma_f32_16x16x32_bf16 v[0:3], v[206:209], v[238:241], v[0:3]
	v_mfma_f32_16x16x32_bf16 v[48:51], v[202:205], v[218:221], v[48:51]
	v_mfma_f32_16x16x32_bf16 v[40:43], v[210:213], v[218:221], v[40:43]
	v_mfma_f32_16x16x32_bf16 v[32:35], v[202:205], v[226:229], v[32:35]
	v_mfma_f32_16x16x32_bf16 v[24:27], v[210:213], v[226:229], v[24:27]
	v_mfma_f32_16x16x32_bf16 v[16:19], v[202:205], v[234:237], v[16:19]
	v_mfma_f32_16x16x32_bf16 v[8:11], v[210:213], v[234:237], v[8:11]
	v_mfma_f32_16x16x32_bf16 v[4:7], v[202:205], v[242:245], v[4:7]
	v_mfma_f32_16x16x32_bf16 v[0:3], v[210:213], v[242:245], v[0:3]
	s_setprio 0
	s_barrier
	s_add_i32 s51, 0, 0x18000
	v_add_u32_e32 v166, s51, v176
	s_add_i32 s70, 0, 0x1c000
	ds_read_b128 v[182:185], v166
	ds_read_b128 v[186:189], v166 offset:1024
	ds_read_b128 v[190:193], v166 offset:2048
	ds_read_b128 v[194:197], v166 offset:3072
	v_add_u32_e32 v166, s70, v176
	ds_read_b128 v[198:201], v166
	ds_read_b128 v[202:205], v166 offset:1024
	ds_read_b128 v[206:209], v166 offset:2048
	ds_read_b128 v[210:213], v166 offset:3072
	s_add_u32 s30, s30, 0x40000
	s_addc_u32 s31, s31, 0
	s_mov_b32 m0, s56
	v_lshl_add_u64 v[166:167], s[30:31], 0, v[138:139]
	ds_read_b128 v[214:217], v179 offset:32768
	ds_read_b128 v[218:221], v179 offset:33792
	ds_read_b128 v[222:225], v179 offset:34816
	ds_read_b128 v[226:229], v179 offset:35840
	ds_read_b128 v[230:233], v179 offset:36864
	ds_read_b128 v[234:237], v179 offset:37888
	ds_read_b128 v[238:241], v179 offset:38912
	ds_read_b128 v[242:245], v179 offset:39936
	global_load_lds_dwordx4 v[166:167], off
	v_lshl_add_u64 v[166:167], s[30:31], 0, v[134:135]
	s_mov_b32 m0, s57
	s_nop 0
	global_load_lds_dwordx4 v[166:167], off
	s_waitcnt vmcnt(8)
	s_waitcnt lgkmcnt(0)
	s_barrier
	s_setprio 1
	v_mfma_f32_16x16x32_bf16 v[124:127], v[182:185], v[214:217], v[124:127]
	v_mfma_f32_16x16x32_bf16 v[120:123], v[190:193], v[214:217], v[120:123]
	v_mfma_f32_16x16x32_bf16 v[116:119], v[182:185], v[222:225], v[116:119]
	v_mfma_f32_16x16x32_bf16 v[108:111], v[190:193], v[222:225], v[108:111]
	v_mfma_f32_16x16x32_bf16 v[100:103], v[182:185], v[230:233], v[100:103]
	v_mfma_f32_16x16x32_bf16 v[92:95], v[190:193], v[230:233], v[92:95]
	v_mfma_f32_16x16x32_bf16 v[84:87], v[182:185], v[238:241], v[84:87]
	v_mfma_f32_16x16x32_bf16 v[76:79], v[190:193], v[238:241], v[76:79]
	v_mfma_f32_16x16x32_bf16 v[124:127], v[186:189], v[218:221], v[124:127]
	v_mfma_f32_16x16x32_bf16 v[120:123], v[194:197], v[218:221], v[120:123]
	v_mfma_f32_16x16x32_bf16 v[116:119], v[186:189], v[226:229], v[116:119]
	v_mfma_f32_16x16x32_bf16 v[108:111], v[194:197], v[226:229], v[108:111]
	v_mfma_f32_16x16x32_bf16 v[100:103], v[186:189], v[234:237], v[100:103]
	v_mfma_f32_16x16x32_bf16 v[92:95], v[194:197], v[234:237], v[92:95]
	v_mfma_f32_16x16x32_bf16 v[84:87], v[186:189], v[242:245], v[84:87]
	v_mfma_f32_16x16x32_bf16 v[76:79], v[194:197], v[242:245], v[76:79]
	v_mfma_f32_16x16x32_bf16 v[112:115], v[198:201], v[214:217], v[112:115]
	v_mfma_f32_16x16x32_bf16 v[104:107], v[206:209], v[214:217], v[104:107]
	v_mfma_f32_16x16x32_bf16 v[96:99], v[198:201], v[222:225], v[96:99]
	v_mfma_f32_16x16x32_bf16 v[88:91], v[206:209], v[222:225], v[88:91]
	v_mfma_f32_16x16x32_bf16 v[80:83], v[198:201], v[230:233], v[80:83]
	v_mfma_f32_16x16x32_bf16 v[72:75], v[206:209], v[230:233], v[72:75]
	v_mfma_f32_16x16x32_bf16 v[68:71], v[198:201], v[238:241], v[68:71]
	v_mfma_f32_16x16x32_bf16 v[64:67], v[206:209], v[238:241], v[64:67]
	v_mfma_f32_16x16x32_bf16 v[112:115], v[202:205], v[218:221], v[112:115]
	v_mfma_f32_16x16x32_bf16 v[104:107], v[210:213], v[218:221], v[104:107]
	v_mfma_f32_16x16x32_bf16 v[96:99], v[202:205], v[226:229], v[96:99]
	v_mfma_f32_16x16x32_bf16 v[88:91], v[210:213], v[226:229], v[88:91]
	v_mfma_f32_16x16x32_bf16 v[80:83], v[202:205], v[234:237], v[80:83]
	v_mfma_f32_16x16x32_bf16 v[72:75], v[210:213], v[234:237], v[72:75]
	v_mfma_f32_16x16x32_bf16 v[68:71], v[202:205], v[242:245], v[68:71]
	v_mfma_f32_16x16x32_bf16 v[64:67], v[210:213], v[242:245], v[64:67]
	s_setprio 0
	s_barrier
	s_add_i32 s30, s51, s15
	v_lshl_add_u64 v[154:155], v[154:155], 0, s[6:7]
	s_mov_b32 m0, s30
	ds_read_b128 v[214:217], v179 offset:49152
	ds_read_b128 v[218:221], v179 offset:50176
	ds_read_b128 v[222:225], v179 offset:51200
	ds_read_b128 v[226:229], v179 offset:52224
	ds_read_b128 v[230:233], v179 offset:53248
	ds_read_b128 v[234:237], v179 offset:54272
	ds_read_b128 v[238:241], v179 offset:55296
	ds_read_b128 v[242:245], v179 offset:56320
	global_load_lds_dwordx4 v[154:155], off
	s_add_i32 m0, s30, 0x2000
	s_add_u32 s30, s46, 0x40080
	v_lshl_add_u64 v[154:155], v[246:247], 0, s[6:7]
	s_addc_u32 s31, s47, 0
	s_add_i32 s46, s70, s15
	global_load_lds_dwordx4 v[154:155], off
	v_lshl_add_u64 v[154:155], s[30:31], 0, v[136:137]
	s_mov_b32 m0, s46
	s_nop 0
	global_load_lds_dwordx4 v[154:155], off
	v_lshl_add_u64 v[154:155], s[30:31], 0, v[132:133]
	s_add_i32 m0, s46, 0x2000
	s_nop 0
	global_load_lds_dwordx4 v[154:155], off
	v_lshl_add_u64 v[154:155], v[248:249], 0, s[6:7]
	s_mov_b32 m0, s59
	s_nop 0
	global_load_lds_dwordx4 v[154:155], off
	v_lshl_add_u64 v[154:155], v[250:251], 0, s[6:7]
	s_mov_b32 m0, s60
	s_nop 0
	global_load_lds_dwordx4 v[154:155], off
	s_waitcnt vmcnt(8)
	s_waitcnt lgkmcnt(0)
	s_barrier
	s_setprio 1
	v_mfma_f32_16x16x32_bf16 v[60:63], v[182:185], v[214:217], v[60:63]
	v_mfma_f32_16x16x32_bf16 v[56:59], v[190:193], v[214:217], v[56:59]
	v_mfma_f32_16x16x32_bf16 v[52:55], v[182:185], v[222:225], v[52:55]
	v_mfma_f32_16x16x32_bf16 v[44:47], v[190:193], v[222:225], v[44:47]
	v_mfma_f32_16x16x32_bf16 v[36:39], v[182:185], v[230:233], v[36:39]
	v_mfma_f32_16x16x32_bf16 v[28:31], v[190:193], v[230:233], v[28:31]
	v_mfma_f32_16x16x32_bf16 v[20:23], v[182:185], v[238:241], v[20:23]
	v_mfma_f32_16x16x32_bf16 v[12:15], v[190:193], v[238:241], v[12:15]
	v_mfma_f32_16x16x32_bf16 v[60:63], v[186:189], v[218:221], v[60:63]
	v_mfma_f32_16x16x32_bf16 v[56:59], v[194:197], v[218:221], v[56:59]
	v_mfma_f32_16x16x32_bf16 v[52:55], v[186:189], v[226:229], v[52:55]
	v_mfma_f32_16x16x32_bf16 v[44:47], v[194:197], v[226:229], v[44:47]
	v_mfma_f32_16x16x32_bf16 v[36:39], v[186:189], v[234:237], v[36:39]
	v_mfma_f32_16x16x32_bf16 v[28:31], v[194:197], v[234:237], v[28:31]
	v_mfma_f32_16x16x32_bf16 v[20:23], v[186:189], v[242:245], v[20:23]
	v_mfma_f32_16x16x32_bf16 v[12:15], v[194:197], v[242:245], v[12:15]
	v_mfma_f32_16x16x32_bf16 v[48:51], v[198:201], v[214:217], v[48:51]
	v_mfma_f32_16x16x32_bf16 v[40:43], v[206:209], v[214:217], v[40:43]
	v_mfma_f32_16x16x32_bf16 v[32:35], v[198:201], v[222:225], v[32:35]
	v_mfma_f32_16x16x32_bf16 v[24:27], v[206:209], v[222:225], v[24:27]
	v_mfma_f32_16x16x32_bf16 v[16:19], v[198:201], v[230:233], v[16:19]
	v_mfma_f32_16x16x32_bf16 v[8:11], v[206:209], v[230:233], v[8:11]
	v_mfma_f32_16x16x32_bf16 v[4:7], v[198:201], v[238:241], v[4:7]
	v_mfma_f32_16x16x32_bf16 v[0:3], v[206:209], v[238:241], v[0:3]
	v_mfma_f32_16x16x32_bf16 v[48:51], v[202:205], v[218:221], v[48:51]
	v_mfma_f32_16x16x32_bf16 v[40:43], v[210:213], v[218:221], v[40:43]
	v_mfma_f32_16x16x32_bf16 v[32:35], v[202:205], v[226:229], v[32:35]
	v_mfma_f32_16x16x32_bf16 v[24:27], v[210:213], v[226:229], v[24:27]
	v_mfma_f32_16x16x32_bf16 v[16:19], v[202:205], v[234:237], v[16:19]
	v_mfma_f32_16x16x32_bf16 v[8:11], v[210:213], v[234:237], v[8:11]
	v_mfma_f32_16x16x32_bf16 v[4:7], v[202:205], v[242:245], v[4:7]
	v_mfma_f32_16x16x32_bf16 v[0:3], v[210:213], v[242:245], v[0:3]
	s_setprio 0
	s_barrier
	s_add_i32 s50, s50, 2
	s_add_u32 s44, s44, 0x100
	s_addc_u32 s45, s45, 0
	s_add_u32 s48, s48, 0x100
	s_addc_u32 s49, s49, 0
	s_cmp_gt_u32 s50, 13
	s_cbranch_scc0 .LBB0_738
	s_and_b64 vcc, exec, s[8:9]
	s_cbranch_vccz .LBB0_741
	s_barrier

.LBB0_758:
	ds_read_b128 v[174:177], v155
	ds_read_b128 v[178:181], v155 offset:1024
	ds_read_b128 v[182:185], v155 offset:2048
	ds_read_b128 v[186:189], v155 offset:3072
	ds_read_b128 v[190:193], v171
	ds_read_b128 v[194:197], v171 offset:1024
	ds_read_b128 v[198:201], v171 offset:2048
	ds_read_b128 v[202:205], v171 offset:3072
	s_add_u32 s44, s42, 0xfffe0080
	s_addc_u32 s45, s43, -1
	s_cmp_eq_u32 s50, 4
	s_cselect_b32 s47, s35, s45
	s_cselect_b32 s46, s36, s44
	s_cselect_b32 s45, s31, s49
	s_cselect_b32 s44, s37, s48
	v_lshl_add_u64 v[130:131], s[42:43], 0, v[144:145]
	s_add_i32 m0, s54, 0xc000
	ds_read_b128 v[206:209], v172
	ds_read_b128 v[210:213], v172 offset:1024
	ds_read_b128 v[214:217], v172 offset:2048
	ds_read_b128 v[218:221], v172 offset:3072
	ds_read_b128 v[222:225], v172 offset:4096
	ds_read_b128 v[226:229], v172 offset:5120
	ds_read_b128 v[230:233], v172 offset:6144
	ds_read_b128 v[234:237], v172 offset:7168
	global_load_lds_dwordx4 v[130:131], off
	v_lshl_add_u64 v[130:131], s[42:43], 0, v[146:147]
	s_add_i32 m0, s54, 0xe000
	s_nop 0
	global_load_lds_dwordx4 v[130:131], off
	s_waitcnt vmcnt(8)
	s_waitcnt lgkmcnt(0)
	s_barrier
	s_setprio 1
	v_mfma_f32_16x16x32_bf16 v[124:127], v[174:177], v[206:209], v[124:127]
	v_mfma_f32_16x16x32_bf16 v[120:123], v[182:185], v[206:209], v[120:123]
	v_mfma_f32_16x16x32_bf16 v[116:119], v[174:177], v[214:217], v[116:119]
	v_mfma_f32_16x16x32_bf16 v[112:115], v[182:185], v[214:217], v[112:115]
	v_mfma_f32_16x16x32_bf16 v[100:103], v[174:177], v[222:225], v[100:103]
	v_mfma_f32_16x16x32_bf16 v[96:99], v[182:185], v[222:225], v[96:99]
	v_mfma_f32_16x16x32_bf16 v[84:87], v[174:177], v[230:233], v[84:87]
	v_mfma_f32_16x16x32_bf16 v[80:83], v[182:185], v[230:233], v[80:83]
	v_mfma_f32_16x16x32_bf16 v[124:127], v[178:181], v[210:213], v[124:127]
	v_mfma_f32_16x16x32_bf16 v[120:123], v[186:189], v[210:213], v[120:123]
	v_mfma_f32_16x16x32_bf16 v[116:119], v[178:181], v[218:221], v[116:119]
	v_mfma_f32_16x16x32_bf16 v[112:115], v[186:189], v[218:221], v[112:115]
	v_mfma_f32_16x16x32_bf16 v[100:103], v[178:181], v[226:229], v[100:103]
	v_mfma_f32_16x16x32_bf16 v[96:99], v[186:189], v[226:229], v[96:99]
	v_mfma_f32_16x16x32_bf16 v[84:87], v[178:181], v[234:237], v[84:87]
	v_mfma_f32_16x16x32_bf16 v[80:83], v[186:189], v[234:237], v[80:83]
	v_mfma_f32_16x16x32_bf16 v[108:111], v[190:193], v[206:209], v[108:111]
	v_mfma_f32_16x16x32_bf16 v[104:107], v[198:201], v[206:209], v[104:107]
	v_mfma_f32_16x16x32_bf16 v[92:95], v[190:193], v[214:217], v[92:95]
	v_mfma_f32_16x16x32_bf16 v[88:91], v[198:201], v[214:217], v[88:91]
	v_mfma_f32_16x16x32_bf16 v[76:79], v[190:193], v[222:225], v[76:79]
	v_mfma_f32_16x16x32_bf16 v[72:75], v[198:201], v[222:225], v[72:75]
	v_mfma_f32_16x16x32_bf16 v[68:71], v[190:193], v[230:233], v[68:71]
	v_mfma_f32_16x16x32_bf16 v[64:67], v[198:201], v[230:233], v[64:67]
	v_mfma_f32_16x16x32_bf16 v[108:111], v[194:197], v[210:213], v[108:111]
	v_mfma_f32_16x16x32_bf16 v[104:107], v[202:205], v[210:213], v[104:107]
	v_mfma_f32_16x16x32_bf16 v[92:95], v[194:197], v[218:221], v[92:95]
	v_mfma_f32_16x16x32_bf16 v[88:91], v[202:205], v[218:221], v[88:91]
	v_mfma_f32_16x16x32_bf16 v[76:79], v[194:197], v[226:229], v[76:79]
	v_mfma_f32_16x16x32_bf16 v[72:75], v[202:205], v[226:229], v[72:75]
	v_mfma_f32_16x16x32_bf16 v[68:71], v[194:197], v[234:237], v[68:71]
	v_mfma_f32_16x16x32_bf16 v[64:67], v[202:205], v[234:237], v[64:67]
	s_setprio 0
	s_barrier
	s_add_i32 s51, s63, s28
	v_lshl_add_u64 v[130:131], s[44:45], 0, v[136:137]
	s_mov_b32 m0, s51
	ds_read_b128 v[206:209], v172 offset:16384
	ds_read_b128 v[210:213], v172 offset:17408
	ds_read_b128 v[214:217], v172 offset:18432
	ds_read_b128 v[218:221], v172 offset:19456
	ds_read_b128 v[222:225], v172 offset:20480
	ds_read_b128 v[226:229], v172 offset:21504
	ds_read_b128 v[230:233], v172 offset:22528
	ds_read_b128 v[234:237], v172 offset:23552
	global_load_lds_dwordx4 v[130:131], off
	s_add_i32 m0, s51, 0x2000
	s_add_u32 s70, s44, 0x20000
	v_lshl_add_u64 v[166:167], s[44:45], 0, v[132:133]
	s_addc_u32 s71, s45, 0
	s_add_i32 s51, s64, s28
	global_load_lds_dwordx4 v[166:167], off
	v_lshl_add_u64 v[238:239], s[70:71], 0, v[136:137]
	s_mov_b32 m0, s51
	v_lshl_add_u64 v[240:241], s[46:47], 0, v[134:135]
	global_load_lds_dwordx4 v[238:239], off
	v_lshl_add_u64 v[238:239], s[70:71], 0, v[132:133]
	s_add_i32 m0, s51, 0x2000
	s_nop 0
	global_load_lds_dwordx4 v[238:239], off
	v_lshl_add_u64 v[238:239], s[46:47], 0, v[138:139]
	s_mov_b32 m0, s54
	s_nop 0
	global_load_lds_dwordx4 v[238:239], off
	s_mov_b32 m0, s55
	s_nop 0
	global_load_lds_dwordx4 v[240:241], off
	s_waitcnt vmcnt(8)
	s_waitcnt lgkmcnt(0)
	s_barrier
	s_setprio 1
	v_mfma_f32_16x16x32_bf16 v[60:63], v[174:177], v[206:209], v[60:63]
	v_mfma_f32_16x16x32_bf16 v[56:59], v[182:185], v[206:209], v[56:59]
	v_mfma_f32_16x16x32_bf16 v[52:55], v[174:177], v[214:217], v[52:55]
	v_mfma_f32_16x16x32_bf16 v[48:51], v[182:185], v[214:217], v[48:51]
	v_mfma_f32_16x16x32_bf16 v[36:39], v[174:177], v[222:225], v[36:39]
	v_mfma_f32_16x16x32_bf16 v[32:35], v[182:185], v[222:225], v[32:35]
	v_mfma_f32_16x16x32_bf16 v[20:23], v[174:177], v[230:233], v[20:23]
	v_mfma_f32_16x16x32_bf16 v[16:19], v[182:185], v[230:233], v[16:19]
	v_mfma_f32_16x16x32_bf16 v[60:63], v[178:181], v[210:213], v[60:63]
	v_mfma_f32_16x16x32_bf16 v[56:59], v[186:189], v[210:213], v[56:59]
	v_mfma_f32_16x16x32_bf16 v[52:55], v[178:181], v[218:221], v[52:55]
	v_mfma_f32_16x16x32_bf16 v[48:51], v[186:189], v[218:221], v[48:51]
	v_mfma_f32_16x16x32_bf16 v[36:39], v[178:181], v[226:229], v[36:39]
	v_mfma_f32_16x16x32_bf16 v[32:35], v[186:189], v[226:229], v[32:35]
	v_mfma_f32_16x16x32_bf16 v[20:23], v[178:181], v[234:237], v[20:23]
	v_mfma_f32_16x16x32_bf16 v[16:19], v[186:189], v[234:237], v[16:19]
	v_mfma_f32_16x16x32_bf16 v[44:47], v[190:193], v[206:209], v[44:47]
	v_mfma_f32_16x16x32_bf16 v[40:43], v[198:201], v[206:209], v[40:43]
	v_mfma_f32_16x16x32_bf16 v[28:31], v[190:193], v[214:217], v[28:31]
	v_mfma_f32_16x16x32_bf16 v[24:27], v[198:201], v[214:217], v[24:27]
	v_mfma_f32_16x16x32_bf16 v[12:15], v[190:193], v[222:225], v[12:15]
	v_mfma_f32_16x16x32_bf16 v[8:11], v[198:201], v[222:225], v[8:11]
	v_mfma_f32_16x16x32_bf16 v[4:7], v[190:193], v[230:233], v[4:7]
	v_mfma_f32_16x16x32_bf16 v[0:3], v[198:201], v[230:233], v[0:3]
	v_mfma_f32_16x16x32_bf16 v[44:47], v[194:197], v[210:213], v[44:47]
	v_mfma_f32_16x16x32_bf16 v[40:43], v[202:205], v[210:213], v[40:43]
	v_mfma_f32_16x16x32_bf16 v[28:31], v[194:197], v[218:221], v[28:31]
	v_mfma_f32_16x16x32_bf16 v[24:27], v[202:205], v[218:221], v[24:27]
	v_mfma_f32_16x16x32_bf16 v[12:15], v[194:197], v[226:229], v[12:15]
	v_mfma_f32_16x16x32_bf16 v[8:11], v[202:205], v[226:229], v[8:11]
	v_mfma_f32_16x16x32_bf16 v[4:7], v[194:197], v[234:237], v[4:7]
	v_mfma_f32_16x16x32_bf16 v[0:3], v[202:205], v[234:237], v[0:3]
	s_setprio 0
	s_barrier
	s_add_i32 s51, 0, 0x18000
	s_add_i32 s70, 0, 0x1c000
	v_add_u32_e32 v186, s51, v153
	v_add_u32_e32 v202, s70, v153
	ds_read_b128 v[174:177], v186
	ds_read_b128 v[178:181], v186 offset:1024
	ds_read_b128 v[182:185], v186 offset:2048
	ds_read_b128 v[186:189], v186 offset:3072
	ds_read_b128 v[190:193], v202
	ds_read_b128 v[194:197], v202 offset:1024
	ds_read_b128 v[198:201], v202 offset:2048
	ds_read_b128 v[202:205], v202 offset:3072
	s_add_u32 s46, s46, 0x20000
	s_addc_u32 s47, s47, 0
	s_mov_b32 m0, s56
	v_lshl_add_u64 v[242:243], s[46:47], 0, v[138:139]
	ds_read_b128 v[206:209], v172 offset:32768
	ds_read_b128 v[210:213], v172 offset:33792
	ds_read_b128 v[214:217], v172 offset:34816
	ds_read_b128 v[218:221], v172 offset:35840
	ds_read_b128 v[222:225], v172 offset:36864
	ds_read_b128 v[226:229], v172 offset:37888
	ds_read_b128 v[230:233], v172 offset:38912
	ds_read_b128 v[234:237], v172 offset:39936
	global_load_lds_dwordx4 v[242:243], off
	v_lshl_add_u64 v[242:243], s[46:47], 0, v[134:135]
	s_mov_b32 m0, s57
	s_nop 0
	global_load_lds_dwordx4 v[242:243], off
	s_waitcnt vmcnt(8)
	s_waitcnt lgkmcnt(0)
	s_barrier
	s_setprio 1
	v_mfma_f32_16x16x32_bf16 v[124:127], v[174:177], v[206:209], v[124:127]
	v_mfma_f32_16x16x32_bf16 v[120:123], v[182:185], v[206:209], v[120:123]
	v_mfma_f32_16x16x32_bf16 v[116:119], v[174:177], v[214:217], v[116:119]
	v_mfma_f32_16x16x32_bf16 v[112:115], v[182:185], v[214:217], v[112:115]
	v_mfma_f32_16x16x32_bf16 v[100:103], v[174:177], v[222:225], v[100:103]
	v_mfma_f32_16x16x32_bf16 v[96:99], v[182:185], v[222:225], v[96:99]
	v_mfma_f32_16x16x32_bf16 v[84:87], v[174:177], v[230:233], v[84:87]
	v_mfma_f32_16x16x32_bf16 v[80:83], v[182:185], v[230:233], v[80:83]
	v_mfma_f32_16x16x32_bf16 v[124:127], v[178:181], v[210:213], v[124:127]
	v_mfma_f32_16x16x32_bf16 v[120:123], v[186:189], v[210:213], v[120:123]
	v_mfma_f32_16x16x32_bf16 v[116:119], v[178:181], v[218:221], v[116:119]
	v_mfma_f32_16x16x32_bf16 v[112:115], v[186:189], v[218:221], v[112:115]
	v_mfma_f32_16x16x32_bf16 v[100:103], v[178:181], v[226:229], v[100:103]
	v_mfma_f32_16x16x32_bf16 v[96:99], v[186:189], v[226:229], v[96:99]
	v_mfma_f32_16x16x32_bf16 v[84:87], v[178:181], v[234:237], v[84:87]
	v_mfma_f32_16x16x32_bf16 v[80:83], v[186:189], v[234:237], v[80:83]
	v_mfma_f32_16x16x32_bf16 v[108:111], v[190:193], v[206:209], v[108:111]
	v_mfma_f32_16x16x32_bf16 v[104:107], v[198:201], v[206:209], v[104:107]
	v_mfma_f32_16x16x32_bf16 v[92:95], v[190:193], v[214:217], v[92:95]
	v_mfma_f32_16x16x32_bf16 v[88:91], v[198:201], v[214:217], v[88:91]
	v_mfma_f32_16x16x32_bf16 v[76:79], v[190:193], v[222:225], v[76:79]
	v_mfma_f32_16x16x32_bf16 v[72:75], v[198:201], v[222:225], v[72:75]
	v_mfma_f32_16x16x32_bf16 v[68:71], v[190:193], v[230:233], v[68:71]
	v_mfma_f32_16x16x32_bf16 v[64:67], v[198:201], v[230:233], v[64:67]
	v_mfma_f32_16x16x32_bf16 v[108:111], v[194:197], v[210:213], v[108:111]
	v_mfma_f32_16x16x32_bf16 v[104:107], v[202:205], v[210:213], v[104:107]
	v_mfma_f32_16x16x32_bf16 v[92:95], v[194:197], v[218:221], v[92:95]
	v_mfma_f32_16x16x32_bf16 v[88:91], v[202:205], v[218:221], v[88:91]
	v_mfma_f32_16x16x32_bf16 v[76:79], v[194:197], v[226:229], v[76:79]
	v_mfma_f32_16x16x32_bf16 v[72:75], v[202:205], v[226:229], v[72:75]
	v_mfma_f32_16x16x32_bf16 v[68:71], v[194:197], v[234:237], v[68:71]
	v_mfma_f32_16x16x32_bf16 v[64:67], v[202:205], v[234:237], v[64:67]
	s_setprio 0
	s_barrier
	s_add_i32 s46, s51, s28
	v_lshl_add_u64 v[130:131], v[130:131], 0, s[8:9]
	s_mov_b32 m0, s46
	ds_read_b128 v[206:209], v172 offset:49152
	ds_read_b128 v[210:213], v172 offset:50176
	ds_read_b128 v[214:217], v172 offset:51200
	ds_read_b128 v[218:221], v172 offset:52224
	ds_read_b128 v[222:225], v172 offset:53248
	ds_read_b128 v[226:229], v172 offset:54272
	ds_read_b128 v[230:233], v172 offset:55296
	ds_read_b128 v[234:237], v172 offset:56320
	global_load_lds_dwordx4 v[130:131], off
	s_add_i32 m0, s46, 0x2000
	s_add_u32 s44, s44, 0x20080
	v_lshl_add_u64 v[130:131], v[166:167], 0, s[8:9]
	s_addc_u32 s45, s45, 0
	s_add_i32 s46, s70, s28
	global_load_lds_dwordx4 v[130:131], off
	v_lshl_add_u64 v[130:131], s[44:45], 0, v[136:137]
	s_mov_b32 m0, s46
	s_nop 0
	global_load_lds_dwordx4 v[130:131], off
	v_lshl_add_u64 v[130:131], s[44:45], 0, v[132:133]
	s_add_i32 m0, s46, 0x2000
	s_nop 0
	global_load_lds_dwordx4 v[130:131], off
	v_lshl_add_u64 v[130:131], v[238:239], 0, s[8:9]
	s_mov_b32 m0, s60
	s_nop 0
	global_load_lds_dwordx4 v[130:131], off
	v_lshl_add_u64 v[130:131], v[240:241], 0, s[8:9]
	s_mov_b32 m0, s61
	s_nop 0
	global_load_lds_dwordx4 v[130:131], off
	s_waitcnt vmcnt(8)
	s_waitcnt lgkmcnt(0)
	s_barrier
	s_setprio 1
	v_mfma_f32_16x16x32_bf16 v[60:63], v[174:177], v[206:209], v[60:63]
	v_mfma_f32_16x16x32_bf16 v[56:59], v[182:185], v[206:209], v[56:59]
	v_mfma_f32_16x16x32_bf16 v[52:55], v[174:177], v[214:217], v[52:55]
	v_mfma_f32_16x16x32_bf16 v[48:51], v[182:185], v[214:217], v[48:51]
	v_mfma_f32_16x16x32_bf16 v[36:39], v[174:177], v[222:225], v[36:39]
	v_mfma_f32_16x16x32_bf16 v[32:35], v[182:185], v[222:225], v[32:35]
	v_mfma_f32_16x16x32_bf16 v[20:23], v[174:177], v[230:233], v[20:23]
	v_mfma_f32_16x16x32_bf16 v[16:19], v[182:185], v[230:233], v[16:19]
	v_mfma_f32_16x16x32_bf16 v[60:63], v[178:181], v[210:213], v[60:63]
	v_mfma_f32_16x16x32_bf16 v[56:59], v[186:189], v[210:213], v[56:59]
	v_mfma_f32_16x16x32_bf16 v[52:55], v[178:181], v[218:221], v[52:55]
	v_mfma_f32_16x16x32_bf16 v[48:51], v[186:189], v[218:221], v[48:51]
	v_mfma_f32_16x16x32_bf16 v[36:39], v[178:181], v[226:229], v[36:39]
	v_mfma_f32_16x16x32_bf16 v[32:35], v[186:189], v[226:229], v[32:35]
	v_mfma_f32_16x16x32_bf16 v[20:23], v[178:181], v[234:237], v[20:23]
	v_mfma_f32_16x16x32_bf16 v[16:19], v[186:189], v[234:237], v[16:19]
	v_mfma_f32_16x16x32_bf16 v[44:47], v[190:193], v[206:209], v[44:47]
	v_mfma_f32_16x16x32_bf16 v[40:43], v[198:201], v[206:209], v[40:43]
	v_mfma_f32_16x16x32_bf16 v[28:31], v[190:193], v[214:217], v[28:31]
	v_mfma_f32_16x16x32_bf16 v[24:27], v[198:201], v[214:217], v[24:27]
	v_mfma_f32_16x16x32_bf16 v[12:15], v[190:193], v[222:225], v[12:15]
	v_mfma_f32_16x16x32_bf16 v[8:11], v[198:201], v[222:225], v[8:11]
	v_mfma_f32_16x16x32_bf16 v[4:7], v[190:193], v[230:233], v[4:7]
	v_mfma_f32_16x16x32_bf16 v[0:3], v[198:201], v[230:233], v[0:3]
	v_mfma_f32_16x16x32_bf16 v[44:47], v[194:197], v[210:213], v[44:47]
	v_mfma_f32_16x16x32_bf16 v[40:43], v[202:205], v[210:213], v[40:43]
	v_mfma_f32_16x16x32_bf16 v[28:31], v[194:197], v[218:221], v[28:31]
	v_mfma_f32_16x16x32_bf16 v[24:27], v[202:205], v[218:221], v[24:27]
	v_mfma_f32_16x16x32_bf16 v[12:15], v[194:197], v[226:229], v[12:15]
	v_mfma_f32_16x16x32_bf16 v[8:11], v[202:205], v[226:229], v[8:11]
	v_mfma_f32_16x16x32_bf16 v[4:7], v[194:197], v[234:237], v[4:7]
	v_mfma_f32_16x16x32_bf16 v[0:3], v[202:205], v[234:237], v[0:3]
	s_setprio 0
	s_barrier
	s_add_i32 s50, s50, 2
	s_add_u32 s42, s42, 0x100
	s_addc_u32 s43, s43, 0
	s_add_u32 s48, s48, 0x100
	s_addc_u32 s49, s49, 0
	s_cmp_gt_u32 s50, 5
	s_cbranch_scc0 .LBB0_758
	s_and_b64 vcc, exec, s[14:15]
	s_cbranch_vccz .LBB0_761
	s_barrier

.LBB0_778:
	ds_read_b128 v[148:151], v144
	ds_read_b128 v[152:155], v144 offset:1024
	ds_read_b128 v[158:161], v144 offset:2048
	ds_read_b128 v[162:165], v144 offset:3072
	ds_read_b128 v[166:169], v145
	ds_read_b128 v[170:173], v145 offset:1024
	ds_read_b128 v[174:177], v145 offset:2048
	ds_read_b128 v[178:181], v145 offset:3072
	s_add_u32 s42, s40, 0xfffe0080
	s_addc_u32 s43, s41, -1
	s_cmp_eq_u32 s61, 4
	s_cselect_b32 s45, s15, s43
	s_cselect_b32 s44, s46, s42
	s_cselect_b32 s43, s9, s51
	s_cselect_b32 s42, s47, s50
	v_lshl_add_u64 v[214:215], s[40:41], 0, v[134:135]
	s_add_i32 m0, s54, 0xc000
	ds_read_b128 v[182:185], v146
	ds_read_b128 v[186:189], v146 offset:1024
	ds_read_b128 v[190:193], v146 offset:2048
	ds_read_b128 v[194:197], v146 offset:3072
	ds_read_b128 v[198:201], v146 offset:4096
	ds_read_b128 v[202:205], v146 offset:5120
	ds_read_b128 v[206:209], v146 offset:6144
	ds_read_b128 v[210:213], v146 offset:7168
	global_load_lds_dwordx4 v[214:215], off
	v_lshl_add_u64 v[214:215], s[40:41], 0, v[136:137]
	s_add_i32 m0, s54, 0xe000
	s_nop 0
	global_load_lds_dwordx4 v[214:215], off
	s_waitcnt vmcnt(8)
	s_waitcnt lgkmcnt(0)
	s_barrier
	s_setprio 1
	v_mfma_f32_16x16x32_bf16 v[124:127], v[148:151], v[182:185], v[124:127]
	v_mfma_f32_16x16x32_bf16 v[104:107], v[158:161], v[182:185], v[104:107]
	v_mfma_f32_16x16x32_bf16 v[120:123], v[148:151], v[190:193], v[120:123]
	v_mfma_f32_16x16x32_bf16 v[96:99], v[158:161], v[190:193], v[96:99]
	v_mfma_f32_16x16x32_bf16 v[116:119], v[148:151], v[198:201], v[116:119]
	v_mfma_f32_16x16x32_bf16 v[88:91], v[158:161], v[198:201], v[88:91]
	v_mfma_f32_16x16x32_bf16 v[112:115], v[148:151], v[206:209], v[112:115]
	v_mfma_f32_16x16x32_bf16 v[80:83], v[158:161], v[206:209], v[80:83]
	v_mfma_f32_16x16x32_bf16 v[124:127], v[152:155], v[186:189], v[124:127]
	v_mfma_f32_16x16x32_bf16 v[104:107], v[162:165], v[186:189], v[104:107]
	v_mfma_f32_16x16x32_bf16 v[120:123], v[152:155], v[194:197], v[120:123]
	v_mfma_f32_16x16x32_bf16 v[96:99], v[162:165], v[194:197], v[96:99]
	v_mfma_f32_16x16x32_bf16 v[116:119], v[152:155], v[202:205], v[116:119]
	v_mfma_f32_16x16x32_bf16 v[88:91], v[162:165], v[202:205], v[88:91]
	v_mfma_f32_16x16x32_bf16 v[112:115], v[152:155], v[210:213], v[112:115]
	v_mfma_f32_16x16x32_bf16 v[80:83], v[162:165], v[210:213], v[80:83]
	v_mfma_f32_16x16x32_bf16 v[64:67], v[166:169], v[182:185], v[64:67]
	v_mfma_f32_16x16x32_bf16 v[40:43], v[174:177], v[182:185], v[40:43]
	v_mfma_f32_16x16x32_bf16 v[56:59], v[166:169], v[190:193], v[56:59]
	v_mfma_f32_16x16x32_bf16 v[32:35], v[174:177], v[190:193], v[32:35]
	v_mfma_f32_16x16x32_bf16 v[52:55], v[166:169], v[198:201], v[52:55]
	v_mfma_f32_16x16x32_bf16 v[24:27], v[174:177], v[198:201], v[24:27]
	v_mfma_f32_16x16x32_bf16 v[48:51], v[166:169], v[206:209], v[48:51]
	v_mfma_f32_16x16x32_bf16 v[16:19], v[174:177], v[206:209], v[16:19]
	v_mfma_f32_16x16x32_bf16 v[64:67], v[170:173], v[186:189], v[64:67]
	v_mfma_f32_16x16x32_bf16 v[40:43], v[178:181], v[186:189], v[40:43]
	v_mfma_f32_16x16x32_bf16 v[56:59], v[170:173], v[194:197], v[56:59]
	v_mfma_f32_16x16x32_bf16 v[32:35], v[178:181], v[194:197], v[32:35]
	v_mfma_f32_16x16x32_bf16 v[52:55], v[170:173], v[202:205], v[52:55]
	v_mfma_f32_16x16x32_bf16 v[24:27], v[178:181], v[202:205], v[24:27]
	v_mfma_f32_16x16x32_bf16 v[48:51], v[170:173], v[210:213], v[48:51]
	v_mfma_f32_16x16x32_bf16 v[16:19], v[178:181], v[210:213], v[16:19]
	s_setprio 0
	s_barrier
	s_add_i32 s62, s48, s28
	v_lshl_add_u64 v[214:215], s[42:43], 0, v[130:131]
	s_mov_b32 m0, s62
	ds_read_b128 v[182:185], v146 offset:16384
	ds_read_b128 v[186:189], v146 offset:17408
	ds_read_b128 v[190:193], v146 offset:18432
	ds_read_b128 v[194:197], v146 offset:19456
	ds_read_b128 v[198:201], v146 offset:20480
	ds_read_b128 v[202:205], v146 offset:21504
	ds_read_b128 v[206:209], v146 offset:22528
	ds_read_b128 v[210:213], v146 offset:23552
	global_load_lds_dwordx4 v[214:215], off
	s_add_i32 m0, s62, 0x2000
	s_add_u32 s62, s42, 0x20000
	v_lshl_add_u64 v[216:217], s[42:43], 0, v[128:129]
	s_addc_u32 s63, s43, 0
	s_add_i32 s64, s49, s28
	global_load_lds_dwordx4 v[216:217], off
	v_lshl_add_u64 v[218:219], s[62:63], 0, v[130:131]
	s_mov_b32 m0, s64
	v_lshl_add_u64 v[220:221], s[44:45], 0, v[128:129]
	global_load_lds_dwordx4 v[218:219], off
	v_lshl_add_u64 v[218:219], s[62:63], 0, v[128:129]
	s_add_i32 m0, s64, 0x2000
	s_nop 0
	global_load_lds_dwordx4 v[218:219], off
	v_lshl_add_u64 v[218:219], s[44:45], 0, v[130:131]
	s_mov_b32 m0, s54
	s_nop 0
	global_load_lds_dwordx4 v[218:219], off
	s_mov_b32 m0, s55
	s_nop 0
	global_load_lds_dwordx4 v[220:221], off
	s_waitcnt vmcnt(8)
	s_waitcnt lgkmcnt(0)
	s_barrier
	s_setprio 1
	v_mfma_f32_16x16x32_bf16 v[108:111], v[148:151], v[182:185], v[108:111]
	v_mfma_f32_16x16x32_bf16 v[76:79], v[158:161], v[182:185], v[76:79]
	v_mfma_f32_16x16x32_bf16 v[100:103], v[148:151], v[190:193], v[100:103]
	v_mfma_f32_16x16x32_bf16 v[72:75], v[158:161], v[190:193], v[72:75]
	v_mfma_f32_16x16x32_bf16 v[92:95], v[148:151], v[198:201], v[92:95]
	v_mfma_f32_16x16x32_bf16 v[68:71], v[158:161], v[198:201], v[68:71]
	v_mfma_f32_16x16x32_bf16 v[84:87], v[148:151], v[206:209], v[84:87]
	v_mfma_f32_16x16x32_bf16 v[60:63], v[158:161], v[206:209], v[60:63]
	v_mfma_f32_16x16x32_bf16 v[108:111], v[152:155], v[186:189], v[108:111]
	v_mfma_f32_16x16x32_bf16 v[76:79], v[162:165], v[186:189], v[76:79]
	v_mfma_f32_16x16x32_bf16 v[100:103], v[152:155], v[194:197], v[100:103]
	v_mfma_f32_16x16x32_bf16 v[72:75], v[162:165], v[194:197], v[72:75]
	v_mfma_f32_16x16x32_bf16 v[92:95], v[152:155], v[202:205], v[92:95]
	v_mfma_f32_16x16x32_bf16 v[68:71], v[162:165], v[202:205], v[68:71]
	v_mfma_f32_16x16x32_bf16 v[84:87], v[152:155], v[210:213], v[84:87]
	v_mfma_f32_16x16x32_bf16 v[60:63], v[162:165], v[210:213], v[60:63]
	v_mfma_f32_16x16x32_bf16 v[44:47], v[166:169], v[182:185], v[44:47]
	v_mfma_f32_16x16x32_bf16 v[12:15], v[174:177], v[182:185], v[12:15]
	v_mfma_f32_16x16x32_bf16 v[36:39], v[166:169], v[190:193], v[36:39]
	v_mfma_f32_16x16x32_bf16 v[8:11], v[174:177], v[190:193], v[8:11]
	v_mfma_f32_16x16x32_bf16 v[28:31], v[166:169], v[198:201], v[28:31]
	v_mfma_f32_16x16x32_bf16 v[4:7], v[174:177], v[198:201], v[4:7]
	v_mfma_f32_16x16x32_bf16 v[20:23], v[166:169], v[206:209], v[20:23]
	v_mfma_f32_16x16x32_bf16 v[0:3], v[174:177], v[206:209], v[0:3]
	v_mfma_f32_16x16x32_bf16 v[44:47], v[170:173], v[186:189], v[44:47]
	v_mfma_f32_16x16x32_bf16 v[12:15], v[178:181], v[186:189], v[12:15]
	v_mfma_f32_16x16x32_bf16 v[36:39], v[170:173], v[194:197], v[36:39]
	v_mfma_f32_16x16x32_bf16 v[8:11], v[178:181], v[194:197], v[8:11]
	v_mfma_f32_16x16x32_bf16 v[28:31], v[170:173], v[202:205], v[28:31]
	v_mfma_f32_16x16x32_bf16 v[4:7], v[178:181], v[202:205], v[4:7]
	v_mfma_f32_16x16x32_bf16 v[20:23], v[170:173], v[210:213], v[20:23]
	v_mfma_f32_16x16x32_bf16 v[0:3], v[178:181], v[210:213], v[0:3]
	s_setprio 0
	s_barrier
	s_add_i32 s62, 0, 0x18000
	v_add_u32_e32 v147, s62, v143
	s_add_i32 s63, 0, 0x1c000
	ds_read_b128 v[148:151], v147
	ds_read_b128 v[152:155], v147 offset:1024
	ds_read_b128 v[158:161], v147 offset:2048
	ds_read_b128 v[162:165], v147 offset:3072
	v_add_u32_e32 v147, s63, v143
	ds_read_b128 v[166:169], v147
	ds_read_b128 v[170:173], v147 offset:1024
	ds_read_b128 v[174:177], v147 offset:2048
	ds_read_b128 v[178:181], v147 offset:3072
	s_add_u32 s44, s44, 0x20000
	s_addc_u32 s45, s45, 0
	s_mov_b32 m0, s56
	v_lshl_add_u64 v[222:223], s[44:45], 0, v[130:131]
	ds_read_b128 v[182:185], v146 offset:32768
	ds_read_b128 v[186:189], v146 offset:33792
	ds_read_b128 v[190:193], v146 offset:34816
	ds_read_b128 v[194:197], v146 offset:35840
	ds_read_b128 v[198:201], v146 offset:36864
	ds_read_b128 v[202:205], v146 offset:37888
	ds_read_b128 v[206:209], v146 offset:38912
	ds_read_b128 v[210:213], v146 offset:39936
	global_load_lds_dwordx4 v[222:223], off
	v_lshl_add_u64 v[222:223], s[44:45], 0, v[128:129]
	s_mov_b32 m0, s57
	s_nop 0
	global_load_lds_dwordx4 v[222:223], off
	s_waitcnt vmcnt(8)
	s_waitcnt lgkmcnt(0)
	s_barrier
	s_setprio 1
	v_mfma_f32_16x16x32_bf16 v[124:127], v[148:151], v[182:185], v[124:127]
	v_mfma_f32_16x16x32_bf16 v[104:107], v[158:161], v[182:185], v[104:107]
	v_mfma_f32_16x16x32_bf16 v[120:123], v[148:151], v[190:193], v[120:123]
	v_mfma_f32_16x16x32_bf16 v[96:99], v[158:161], v[190:193], v[96:99]
	v_mfma_f32_16x16x32_bf16 v[116:119], v[148:151], v[198:201], v[116:119]
	v_mfma_f32_16x16x32_bf16 v[88:91], v[158:161], v[198:201], v[88:91]
	v_mfma_f32_16x16x32_bf16 v[112:115], v[148:151], v[206:209], v[112:115]
	v_mfma_f32_16x16x32_bf16 v[80:83], v[158:161], v[206:209], v[80:83]
	v_mfma_f32_16x16x32_bf16 v[124:127], v[152:155], v[186:189], v[124:127]
	v_mfma_f32_16x16x32_bf16 v[104:107], v[162:165], v[186:189], v[104:107]
	v_mfma_f32_16x16x32_bf16 v[120:123], v[152:155], v[194:197], v[120:123]
	v_mfma_f32_16x16x32_bf16 v[96:99], v[162:165], v[194:197], v[96:99]
	v_mfma_f32_16x16x32_bf16 v[116:119], v[152:155], v[202:205], v[116:119]
	v_mfma_f32_16x16x32_bf16 v[88:91], v[162:165], v[202:205], v[88:91]
	v_mfma_f32_16x16x32_bf16 v[112:115], v[152:155], v[210:213], v[112:115]
	v_mfma_f32_16x16x32_bf16 v[80:83], v[162:165], v[210:213], v[80:83]
	v_mfma_f32_16x16x32_bf16 v[64:67], v[166:169], v[182:185], v[64:67]
	v_mfma_f32_16x16x32_bf16 v[40:43], v[174:177], v[182:185], v[40:43]
	v_mfma_f32_16x16x32_bf16 v[56:59], v[166:169], v[190:193], v[56:59]
	v_mfma_f32_16x16x32_bf16 v[32:35], v[174:177], v[190:193], v[32:35]
	v_mfma_f32_16x16x32_bf16 v[52:55], v[166:169], v[198:201], v[52:55]
	v_mfma_f32_16x16x32_bf16 v[24:27], v[174:177], v[198:201], v[24:27]
	v_mfma_f32_16x16x32_bf16 v[48:51], v[166:169], v[206:209], v[48:51]
	v_mfma_f32_16x16x32_bf16 v[16:19], v[174:177], v[206:209], v[16:19]
	v_mfma_f32_16x16x32_bf16 v[64:67], v[170:173], v[186:189], v[64:67]
	v_mfma_f32_16x16x32_bf16 v[40:43], v[178:181], v[186:189], v[40:43]
	v_mfma_f32_16x16x32_bf16 v[56:59], v[170:173], v[194:197], v[56:59]
	v_mfma_f32_16x16x32_bf16 v[32:35], v[178:181], v[194:197], v[32:35]
	v_mfma_f32_16x16x32_bf16 v[52:55], v[170:173], v[202:205], v[52:55]
	v_mfma_f32_16x16x32_bf16 v[24:27], v[178:181], v[202:205], v[24:27]
	v_mfma_f32_16x16x32_bf16 v[48:51], v[170:173], v[210:213], v[48:51]
	v_mfma_f32_16x16x32_bf16 v[16:19], v[178:181], v[210:213], v[16:19]
	s_setprio 0
	s_barrier
	s_add_i32 s44, s62, s28
	v_lshl_add_u64 v[214:215], v[214:215], 0, s[4:5]
	s_mov_b32 m0, s44
	ds_read_b128 v[182:185], v146 offset:49152
	ds_read_b128 v[186:189], v146 offset:50176
	ds_read_b128 v[190:193], v146 offset:51200
	ds_read_b128 v[194:197], v146 offset:52224
	ds_read_b128 v[198:201], v146 offset:53248
	ds_read_b128 v[202:205], v146 offset:54272
	ds_read_b128 v[206:209], v146 offset:55296
	ds_read_b128 v[210:213], v146 offset:56320
	global_load_lds_dwordx4 v[214:215], off
	s_add_i32 m0, s44, 0x2000
	s_add_u32 s42, s42, 0x20080
	v_lshl_add_u64 v[214:215], v[216:217], 0, s[4:5]
	s_addc_u32 s43, s43, 0
	s_add_i32 s44, s63, s28
	global_load_lds_dwordx4 v[214:215], off
	v_lshl_add_u64 v[214:215], s[42:43], 0, v[130:131]
	s_mov_b32 m0, s44
	s_nop 0
	global_load_lds_dwordx4 v[214:215], off
	v_lshl_add_u64 v[214:215], s[42:43], 0, v[128:129]
	s_add_i32 m0, s44, 0x2000
	s_nop 0
	global_load_lds_dwordx4 v[214:215], off
	v_lshl_add_u64 v[214:215], v[218:219], 0, s[4:5]
	s_mov_b32 m0, s60
	s_nop 0
	global_load_lds_dwordx4 v[214:215], off
	v_lshl_add_u64 v[214:215], v[220:221], 0, s[4:5]
	s_mov_b32 m0, s36
	s_nop 0
	global_load_lds_dwordx4 v[214:215], off
	s_waitcnt vmcnt(8)
	s_waitcnt lgkmcnt(0)
	s_barrier
	s_setprio 1
	v_mfma_f32_16x16x32_bf16 v[108:111], v[148:151], v[182:185], v[108:111]
	v_mfma_f32_16x16x32_bf16 v[76:79], v[158:161], v[182:185], v[76:79]
	v_mfma_f32_16x16x32_bf16 v[100:103], v[148:151], v[190:193], v[100:103]
	v_mfma_f32_16x16x32_bf16 v[72:75], v[158:161], v[190:193], v[72:75]
	v_mfma_f32_16x16x32_bf16 v[92:95], v[148:151], v[198:201], v[92:95]
	v_mfma_f32_16x16x32_bf16 v[68:71], v[158:161], v[198:201], v[68:71]
	v_mfma_f32_16x16x32_bf16 v[84:87], v[148:151], v[206:209], v[84:87]
	v_mfma_f32_16x16x32_bf16 v[60:63], v[158:161], v[206:209], v[60:63]
	v_mfma_f32_16x16x32_bf16 v[108:111], v[152:155], v[186:189], v[108:111]
	v_mfma_f32_16x16x32_bf16 v[76:79], v[162:165], v[186:189], v[76:79]
	v_mfma_f32_16x16x32_bf16 v[100:103], v[152:155], v[194:197], v[100:103]
	v_mfma_f32_16x16x32_bf16 v[72:75], v[162:165], v[194:197], v[72:75]
	v_mfma_f32_16x16x32_bf16 v[92:95], v[152:155], v[202:205], v[92:95]
	v_mfma_f32_16x16x32_bf16 v[68:71], v[162:165], v[202:205], v[68:71]
	v_mfma_f32_16x16x32_bf16 v[84:87], v[152:155], v[210:213], v[84:87]
	v_mfma_f32_16x16x32_bf16 v[60:63], v[162:165], v[210:213], v[60:63]
	v_mfma_f32_16x16x32_bf16 v[44:47], v[166:169], v[182:185], v[44:47]
	v_mfma_f32_16x16x32_bf16 v[12:15], v[174:177], v[182:185], v[12:15]
	v_mfma_f32_16x16x32_bf16 v[36:39], v[166:169], v[190:193], v[36:39]
	v_mfma_f32_16x16x32_bf16 v[8:11], v[174:177], v[190:193], v[8:11]
	v_mfma_f32_16x16x32_bf16 v[28:31], v[166:169], v[198:201], v[28:31]
	v_mfma_f32_16x16x32_bf16 v[4:7], v[174:177], v[198:201], v[4:7]
	v_mfma_f32_16x16x32_bf16 v[20:23], v[166:169], v[206:209], v[20:23]
	v_mfma_f32_16x16x32_bf16 v[0:3], v[174:177], v[206:209], v[0:3]
	v_mfma_f32_16x16x32_bf16 v[44:47], v[170:173], v[186:189], v[44:47]
	v_mfma_f32_16x16x32_bf16 v[12:15], v[178:181], v[186:189], v[12:15]
	v_mfma_f32_16x16x32_bf16 v[36:39], v[170:173], v[194:197], v[36:39]
	v_mfma_f32_16x16x32_bf16 v[8:11], v[178:181], v[194:197], v[8:11]
	v_mfma_f32_16x16x32_bf16 v[28:31], v[170:173], v[202:205], v[28:31]
	v_mfma_f32_16x16x32_bf16 v[4:7], v[178:181], v[202:205], v[4:7]
	v_mfma_f32_16x16x32_bf16 v[20:23], v[170:173], v[210:213], v[20:23]
	v_mfma_f32_16x16x32_bf16 v[0:3], v[178:181], v[210:213], v[0:3]
	s_setprio 0
	s_barrier
	s_add_i32 s61, s61, 2
	s_add_u32 s40, s40, 0x100
	s_addc_u32 s41, s41, 0
	s_add_u32 s50, s50, 0x100
	s_addc_u32 s51, s51, 0
	s_cmp_gt_u32 s61, 5
	s_cbranch_scc0 .LBB0_778
	s_and_b64 vcc, exec, s[6:7]
	s_cbranch_vccz .LBB0_781
	s_barrier

.LBB0_1141:
	ds_read_b128 v[128:131], v177
	ds_read_b128 v[132:135], v177 offset:1024
	ds_read_b128 v[136:139], v177 offset:2048
	ds_read_b128 v[140:143], v177 offset:3072
	ds_read_b128 v[144:147], v178
	ds_read_b128 v[162:165], v178 offset:1024
	ds_read_b128 v[166:169], v178 offset:2048
	ds_read_b128 v[170:173], v178 offset:3072
	s_add_i32 s49, s45, 2
	s_add_u32 s50, s52, 0xfff00080
	s_addc_u32 s51, s53, -1
	s_cmp_eq_u32 s35, s45
	s_cselect_b32 s57, s41, s51
	s_cselect_b32 s56, s40, s50
	s_cselect_b32 s55, s43, s39
	s_cselect_b32 s54, s42, s37
	v_lshl_add_u64 v[214:215], s[52:53], 0, v[156:157]
	s_add_i32 m0, s47, 0xc000
	ds_read_b128 v[180:183], v179
	ds_read_b128 v[184:187], v179 offset:1024
	ds_read_b128 v[188:191], v179 offset:2048
	ds_read_b128 v[192:195], v179 offset:3072
	ds_read_b128 v[196:199], v179 offset:4096
	ds_read_b128 v[202:205], v179 offset:5120
	ds_read_b128 v[206:209], v179 offset:6144
	ds_read_b128 v[210:213], v179 offset:7168
	global_load_lds_dwordx4 v[214:215], off
	v_lshl_add_u64 v[214:215], s[52:53], 0, v[158:159]
	s_add_i32 m0, s47, 0xe000
	s_nop 0
	global_load_lds_dwordx4 v[214:215], off
	s_waitcnt vmcnt(8)
	s_waitcnt lgkmcnt(0)
	s_barrier
	s_setprio 1
	v_mfma_f32_16x16x32_bf16 v[124:127], v[128:131], v[180:183], v[124:127]
	v_mfma_f32_16x16x32_bf16 v[120:123], v[136:139], v[180:183], v[120:123]
	v_mfma_f32_16x16x32_bf16 v[108:111], v[128:131], v[188:191], v[108:111]
	v_mfma_f32_16x16x32_bf16 v[104:107], v[136:139], v[188:191], v[104:107]
	v_mfma_f32_16x16x32_bf16 v[92:95], v[128:131], v[196:199], v[92:95]
	v_mfma_f32_16x16x32_bf16 v[88:91], v[136:139], v[196:199], v[88:91]
	v_mfma_f32_16x16x32_bf16 v[76:79], v[128:131], v[206:209], v[76:79]
	v_mfma_f32_16x16x32_bf16 v[72:75], v[136:139], v[206:209], v[72:75]
	v_mfma_f32_16x16x32_bf16 v[124:127], v[132:135], v[184:187], v[124:127]
	v_mfma_f32_16x16x32_bf16 v[120:123], v[140:143], v[184:187], v[120:123]
	v_mfma_f32_16x16x32_bf16 v[108:111], v[132:135], v[192:195], v[108:111]
	v_mfma_f32_16x16x32_bf16 v[104:107], v[140:143], v[192:195], v[104:107]
	v_mfma_f32_16x16x32_bf16 v[92:95], v[132:135], v[202:205], v[92:95]
	v_mfma_f32_16x16x32_bf16 v[88:91], v[140:143], v[202:205], v[88:91]
	v_mfma_f32_16x16x32_bf16 v[76:79], v[132:135], v[210:213], v[76:79]
	v_mfma_f32_16x16x32_bf16 v[72:75], v[140:143], v[210:213], v[72:75]
	v_mfma_f32_16x16x32_bf16 v[116:119], v[144:147], v[180:183], v[116:119]
	v_mfma_f32_16x16x32_bf16 v[112:115], v[166:169], v[180:183], v[112:115]
	v_mfma_f32_16x16x32_bf16 v[100:103], v[144:147], v[188:191], v[100:103]
	v_mfma_f32_16x16x32_bf16 v[96:99], v[166:169], v[188:191], v[96:99]
	v_mfma_f32_16x16x32_bf16 v[84:87], v[144:147], v[196:199], v[84:87]
	v_mfma_f32_16x16x32_bf16 v[80:83], v[166:169], v[196:199], v[80:83]
	v_mfma_f32_16x16x32_bf16 v[68:71], v[144:147], v[206:209], v[68:71]
	v_mfma_f32_16x16x32_bf16 v[64:67], v[166:169], v[206:209], v[64:67]
	v_mfma_f32_16x16x32_bf16 v[116:119], v[162:165], v[184:187], v[116:119]
	v_mfma_f32_16x16x32_bf16 v[112:115], v[170:173], v[184:187], v[112:115]
	v_mfma_f32_16x16x32_bf16 v[100:103], v[162:165], v[192:195], v[100:103]
	v_mfma_f32_16x16x32_bf16 v[96:99], v[170:173], v[192:195], v[96:99]
	v_mfma_f32_16x16x32_bf16 v[84:87], v[162:165], v[202:205], v[84:87]
	v_mfma_f32_16x16x32_bf16 v[80:83], v[170:173], v[202:205], v[80:83]
	v_mfma_f32_16x16x32_bf16 v[68:71], v[162:165], v[210:213], v[68:71]
	v_mfma_f32_16x16x32_bf16 v[64:67], v[170:173], v[210:213], v[64:67]
	s_setprio 0
	s_barrier
	s_add_i32 s45, s67, s33
	v_lshl_add_u64 v[214:215], s[54:55], 0, v[150:151]
	s_mov_b32 m0, s45
	ds_read_b128 v[180:183], v179 offset:16384
	ds_read_b128 v[184:187], v179 offset:17408
	ds_read_b128 v[188:191], v179 offset:18432
	ds_read_b128 v[192:195], v179 offset:19456
	ds_read_b128 v[196:199], v179 offset:20480
	ds_read_b128 v[202:205], v179 offset:21504
	ds_read_b128 v[206:209], v179 offset:22528
	ds_read_b128 v[210:213], v179 offset:23552
	global_load_lds_dwordx4 v[214:215], off
	s_add_i32 m0, s45, 0x2000
	s_add_u32 s50, s54, 0x100000
	v_lshl_add_u64 v[216:217], s[54:55], 0, v[154:155]
	s_addc_u32 s51, s55, 0
	s_add_i32 s45, s68, s33
	global_load_lds_dwordx4 v[216:217], off
	v_lshl_add_u64 v[218:219], s[50:51], 0, v[150:151]
	s_mov_b32 m0, s45
	v_lshl_add_u64 v[220:221], s[56:57], 0, v[152:153]
	global_load_lds_dwordx4 v[218:219], off
	v_lshl_add_u64 v[218:219], s[50:51], 0, v[154:155]
	s_add_i32 m0, s45, 0x2000
	s_nop 0
	global_load_lds_dwordx4 v[218:219], off
	v_lshl_add_u64 v[218:219], s[56:57], 0, v[148:149]
	s_mov_b32 m0, s47
	s_nop 0
	global_load_lds_dwordx4 v[218:219], off
	s_mov_b32 m0, s60
	s_nop 0
	global_load_lds_dwordx4 v[220:221], off
	s_waitcnt vmcnt(8)
	s_waitcnt lgkmcnt(0)
	s_barrier
	s_setprio 1
	v_mfma_f32_16x16x32_bf16 v[60:63], v[128:131], v[180:183], v[60:63]
	v_mfma_f32_16x16x32_bf16 v[56:59], v[136:139], v[180:183], v[56:59]
	v_mfma_f32_16x16x32_bf16 v[44:47], v[128:131], v[188:191], v[44:47]
	v_mfma_f32_16x16x32_bf16 v[40:43], v[136:139], v[188:191], v[40:43]
	v_mfma_f32_16x16x32_bf16 v[28:31], v[128:131], v[196:199], v[28:31]
	v_mfma_f32_16x16x32_bf16 v[24:27], v[136:139], v[196:199], v[24:27]
	v_mfma_f32_16x16x32_bf16 v[12:15], v[128:131], v[206:209], v[12:15]
	v_mfma_f32_16x16x32_bf16 v[8:11], v[136:139], v[206:209], v[8:11]
	v_mfma_f32_16x16x32_bf16 v[60:63], v[132:135], v[184:187], v[60:63]
	v_mfma_f32_16x16x32_bf16 v[56:59], v[140:143], v[184:187], v[56:59]
	v_mfma_f32_16x16x32_bf16 v[44:47], v[132:135], v[192:195], v[44:47]
	v_mfma_f32_16x16x32_bf16 v[40:43], v[140:143], v[192:195], v[40:43]
	v_mfma_f32_16x16x32_bf16 v[28:31], v[132:135], v[202:205], v[28:31]
	v_mfma_f32_16x16x32_bf16 v[24:27], v[140:143], v[202:205], v[24:27]
	v_mfma_f32_16x16x32_bf16 v[12:15], v[132:135], v[210:213], v[12:15]
	v_mfma_f32_16x16x32_bf16 v[8:11], v[140:143], v[210:213], v[8:11]
	v_mfma_f32_16x16x32_bf16 v[52:55], v[144:147], v[180:183], v[52:55]
	v_mfma_f32_16x16x32_bf16 v[48:51], v[166:169], v[180:183], v[48:51]
	v_mfma_f32_16x16x32_bf16 v[36:39], v[144:147], v[188:191], v[36:39]
	v_mfma_f32_16x16x32_bf16 v[32:35], v[166:169], v[188:191], v[32:35]
	v_mfma_f32_16x16x32_bf16 v[20:23], v[144:147], v[196:199], v[20:23]
	v_mfma_f32_16x16x32_bf16 v[16:19], v[166:169], v[196:199], v[16:19]
	v_mfma_f32_16x16x32_bf16 v[4:7], v[144:147], v[206:209], v[4:7]
	v_mfma_f32_16x16x32_bf16 v[0:3], v[166:169], v[206:209], v[0:3]
	v_mfma_f32_16x16x32_bf16 v[52:55], v[162:165], v[184:187], v[52:55]
	v_mfma_f32_16x16x32_bf16 v[48:51], v[170:173], v[184:187], v[48:51]
	v_mfma_f32_16x16x32_bf16 v[36:39], v[162:165], v[192:195], v[36:39]
	v_mfma_f32_16x16x32_bf16 v[32:35], v[170:173], v[192:195], v[32:35]
	v_mfma_f32_16x16x32_bf16 v[20:23], v[162:165], v[202:205], v[20:23]
	v_mfma_f32_16x16x32_bf16 v[16:19], v[170:173], v[202:205], v[16:19]
	v_mfma_f32_16x16x32_bf16 v[4:7], v[162:165], v[210:213], v[4:7]
	v_mfma_f32_16x16x32_bf16 v[0:3], v[170:173], v[210:213], v[0:3]
	s_setprio 0
	s_barrier
	s_add_i32 s45, 0, 0x18000
	s_add_i32 s72, 0, 0x1c000
	v_add_u32_e32 v140, s45, v175
	v_add_u32_e32 v170, s72, v175
	ds_read_b128 v[128:131], v140
	ds_read_b128 v[132:135], v140 offset:1024
	ds_read_b128 v[136:139], v140 offset:2048
	ds_read_b128 v[140:143], v140 offset:3072
	ds_read_b128 v[144:147], v170
	ds_read_b128 v[162:165], v170 offset:1024
	ds_read_b128 v[166:169], v170 offset:2048
	ds_read_b128 v[170:173], v170 offset:3072
	s_add_u32 s50, s56, 0x100000
	s_addc_u32 s51, s57, 0
	s_mov_b32 m0, s61
	v_lshl_add_u64 v[222:223], s[50:51], 0, v[148:149]
	ds_read_b128 v[180:183], v179 offset:32768
	ds_read_b128 v[184:187], v179 offset:33792
	ds_read_b128 v[188:191], v179 offset:34816
	ds_read_b128 v[192:195], v179 offset:35840
	ds_read_b128 v[196:199], v179 offset:36864
	ds_read_b128 v[202:205], v179 offset:37888
	ds_read_b128 v[206:209], v179 offset:38912
	ds_read_b128 v[210:213], v179 offset:39936
	global_load_lds_dwordx4 v[222:223], off
	v_lshl_add_u64 v[222:223], s[50:51], 0, v[152:153]
	s_mov_b32 m0, s62
	s_nop 0
	global_load_lds_dwordx4 v[222:223], off
	s_waitcnt vmcnt(8)
	s_waitcnt lgkmcnt(0)
	s_barrier
	s_setprio 1
	v_mfma_f32_16x16x32_bf16 v[124:127], v[128:131], v[180:183], v[124:127]
	v_mfma_f32_16x16x32_bf16 v[120:123], v[136:139], v[180:183], v[120:123]
	v_mfma_f32_16x16x32_bf16 v[108:111], v[128:131], v[188:191], v[108:111]
	v_mfma_f32_16x16x32_bf16 v[104:107], v[136:139], v[188:191], v[104:107]
	v_mfma_f32_16x16x32_bf16 v[92:95], v[128:131], v[196:199], v[92:95]
	v_mfma_f32_16x16x32_bf16 v[88:91], v[136:139], v[196:199], v[88:91]
	v_mfma_f32_16x16x32_bf16 v[76:79], v[128:131], v[206:209], v[76:79]
	v_mfma_f32_16x16x32_bf16 v[72:75], v[136:139], v[206:209], v[72:75]
	v_mfma_f32_16x16x32_bf16 v[124:127], v[132:135], v[184:187], v[124:127]
	v_mfma_f32_16x16x32_bf16 v[120:123], v[140:143], v[184:187], v[120:123]
	v_mfma_f32_16x16x32_bf16 v[108:111], v[132:135], v[192:195], v[108:111]
	v_mfma_f32_16x16x32_bf16 v[104:107], v[140:143], v[192:195], v[104:107]
	v_mfma_f32_16x16x32_bf16 v[92:95], v[132:135], v[202:205], v[92:95]
	v_mfma_f32_16x16x32_bf16 v[88:91], v[140:143], v[202:205], v[88:91]
	v_mfma_f32_16x16x32_bf16 v[76:79], v[132:135], v[210:213], v[76:79]
	v_mfma_f32_16x16x32_bf16 v[72:75], v[140:143], v[210:213], v[72:75]
	v_mfma_f32_16x16x32_bf16 v[116:119], v[144:147], v[180:183], v[116:119]
	v_mfma_f32_16x16x32_bf16 v[112:115], v[166:169], v[180:183], v[112:115]
	v_mfma_f32_16x16x32_bf16 v[100:103], v[144:147], v[188:191], v[100:103]
	v_mfma_f32_16x16x32_bf16 v[96:99], v[166:169], v[188:191], v[96:99]
	v_mfma_f32_16x16x32_bf16 v[84:87], v[144:147], v[196:199], v[84:87]
	v_mfma_f32_16x16x32_bf16 v[80:83], v[166:169], v[196:199], v[80:83]
	v_mfma_f32_16x16x32_bf16 v[68:71], v[144:147], v[206:209], v[68:71]
	v_mfma_f32_16x16x32_bf16 v[64:67], v[166:169], v[206:209], v[64:67]
	v_mfma_f32_16x16x32_bf16 v[116:119], v[162:165], v[184:187], v[116:119]
	v_mfma_f32_16x16x32_bf16 v[112:115], v[170:173], v[184:187], v[112:115]
	v_mfma_f32_16x16x32_bf16 v[100:103], v[162:165], v[192:195], v[100:103]
	v_mfma_f32_16x16x32_bf16 v[96:99], v[170:173], v[192:195], v[96:99]
	v_mfma_f32_16x16x32_bf16 v[84:87], v[162:165], v[202:205], v[84:87]
	v_mfma_f32_16x16x32_bf16 v[80:83], v[170:173], v[202:205], v[80:83]
	v_mfma_f32_16x16x32_bf16 v[68:71], v[162:165], v[210:213], v[68:71]
	v_mfma_f32_16x16x32_bf16 v[64:67], v[170:173], v[210:213], v[64:67]
	s_setprio 0
	s_barrier
	s_add_i32 s45, s45, s33
	v_lshl_add_u64 v[214:215], v[214:215], 0, s[10:11]
	s_mov_b32 m0, s45
	ds_read_b128 v[180:183], v179 offset:49152
	ds_read_b128 v[184:187], v179 offset:50176
	ds_read_b128 v[188:191], v179 offset:51200
	ds_read_b128 v[192:195], v179 offset:52224
	ds_read_b128 v[196:199], v179 offset:53248
	ds_read_b128 v[202:205], v179 offset:54272
	ds_read_b128 v[206:209], v179 offset:55296
	ds_read_b128 v[210:213], v179 offset:56320
	global_load_lds_dwordx4 v[214:215], off
	s_add_i32 m0, s45, 0x2000
	s_add_u32 s50, s54, 0x100080
	v_lshl_add_u64 v[214:215], v[216:217], 0, s[10:11]
	s_addc_u32 s51, s55, 0
	s_add_i32 s45, s72, s33
	global_load_lds_dwordx4 v[214:215], off
	v_lshl_add_u64 v[214:215], s[50:51], 0, v[150:151]
	s_mov_b32 m0, s45
	s_nop 0
	global_load_lds_dwordx4 v[214:215], off
	v_lshl_add_u64 v[214:215], s[50:51], 0, v[154:155]
	s_add_i32 m0, s45, 0x2000
	s_nop 0
	global_load_lds_dwordx4 v[214:215], off
	v_lshl_add_u64 v[214:215], v[218:219], 0, s[10:11]
	s_mov_b32 m0, s63
	s_nop 0
	global_load_lds_dwordx4 v[214:215], off
	v_lshl_add_u64 v[214:215], v[220:221], 0, s[10:11]
	s_mov_b32 m0, s64
	s_nop 0
	global_load_lds_dwordx4 v[214:215], off
	s_waitcnt vmcnt(8)
	s_waitcnt lgkmcnt(0)
	s_barrier
	s_setprio 1
	v_mfma_f32_16x16x32_bf16 v[60:63], v[128:131], v[180:183], v[60:63]
	v_mfma_f32_16x16x32_bf16 v[56:59], v[136:139], v[180:183], v[56:59]
	v_mfma_f32_16x16x32_bf16 v[44:47], v[128:131], v[188:191], v[44:47]
	v_mfma_f32_16x16x32_bf16 v[40:43], v[136:139], v[188:191], v[40:43]
	v_mfma_f32_16x16x32_bf16 v[28:31], v[128:131], v[196:199], v[28:31]
	v_mfma_f32_16x16x32_bf16 v[24:27], v[136:139], v[196:199], v[24:27]
	v_mfma_f32_16x16x32_bf16 v[12:15], v[128:131], v[206:209], v[12:15]
	v_mfma_f32_16x16x32_bf16 v[8:11], v[136:139], v[206:209], v[8:11]
	v_mfma_f32_16x16x32_bf16 v[60:63], v[132:135], v[184:187], v[60:63]
	v_mfma_f32_16x16x32_bf16 v[56:59], v[140:143], v[184:187], v[56:59]
	v_mfma_f32_16x16x32_bf16 v[44:47], v[132:135], v[192:195], v[44:47]
	v_mfma_f32_16x16x32_bf16 v[40:43], v[140:143], v[192:195], v[40:43]
	v_mfma_f32_16x16x32_bf16 v[28:31], v[132:135], v[202:205], v[28:31]
	v_mfma_f32_16x16x32_bf16 v[24:27], v[140:143], v[202:205], v[24:27]
	v_mfma_f32_16x16x32_bf16 v[12:15], v[132:135], v[210:213], v[12:15]
	v_mfma_f32_16x16x32_bf16 v[8:11], v[140:143], v[210:213], v[8:11]
	v_mfma_f32_16x16x32_bf16 v[52:55], v[144:147], v[180:183], v[52:55]
	v_mfma_f32_16x16x32_bf16 v[48:51], v[166:169], v[180:183], v[48:51]
	v_mfma_f32_16x16x32_bf16 v[36:39], v[144:147], v[188:191], v[36:39]
	v_mfma_f32_16x16x32_bf16 v[32:35], v[166:169], v[188:191], v[32:35]
	v_mfma_f32_16x16x32_bf16 v[20:23], v[144:147], v[196:199], v[20:23]
	v_mfma_f32_16x16x32_bf16 v[16:19], v[166:169], v[196:199], v[16:19]
	v_mfma_f32_16x16x32_bf16 v[4:7], v[144:147], v[206:209], v[4:7]
	v_mfma_f32_16x16x32_bf16 v[0:3], v[166:169], v[206:209], v[0:3]
	v_mfma_f32_16x16x32_bf16 v[52:55], v[162:165], v[184:187], v[52:55]
	v_mfma_f32_16x16x32_bf16 v[48:51], v[170:173], v[184:187], v[48:51]
	v_mfma_f32_16x16x32_bf16 v[36:39], v[162:165], v[192:195], v[36:39]
	v_mfma_f32_16x16x32_bf16 v[32:35], v[170:173], v[192:195], v[32:35]
	v_mfma_f32_16x16x32_bf16 v[20:23], v[162:165], v[202:205], v[20:23]
	v_mfma_f32_16x16x32_bf16 v[16:19], v[170:173], v[202:205], v[16:19]
	v_mfma_f32_16x16x32_bf16 v[4:7], v[162:165], v[210:213], v[4:7]
	v_mfma_f32_16x16x32_bf16 v[0:3], v[170:173], v[210:213], v[0:3]
	s_setprio 0
	s_barrier
	s_add_u32 s52, s52, 0x100
	s_addc_u32 s53, s53, 0
	s_add_u32 s37, s37, 0x100
	s_addc_u32 s39, s39, 0
	s_cmp_ge_i32 s49, s48
	s_mov_b32 s45, s49
	s_cbranch_scc0 .LBB0_1141
	s_and_b64 vcc, exec, s[14:15]
	s_cbranch_vccz .LBB0_1144

.LBB0_1299:
	ds_read_b128 v[144:147], v153
	ds_read_b128 v[156:159], v153 offset:1024
	ds_read_b128 v[160:163], v153 offset:2048
	ds_read_b128 v[164:167], v153 offset:3072
	ds_read_b128 v[168:171], v154
	ds_read_b128 v[172:175], v154 offset:1024
	ds_read_b128 v[176:179], v154 offset:2048
	ds_read_b128 v[180:183], v154 offset:3072
	s_add_u32 s36, s34, 0xfff00080
	s_addc_u32 s37, s35, -1
	s_cmp_eq_u32 s57, 60
	s_cselect_b32 s39, s13, s37
	s_cselect_b32 s38, s53, s36
	s_cselect_b32 s37, s11, s56
	s_cselect_b32 s36, s54, s55
	v_lshl_add_u64 v[218:219], s[34:35], 0, v[136:137]
	s_add_i32 m0, s31, 0xc000
	ds_read_b128 v[184:187], v155
	ds_read_b128 v[188:191], v155 offset:1024
	ds_read_b128 v[192:195], v155 offset:2048
	ds_read_b128 v[196:199], v155 offset:3072
	ds_read_b128 v[202:205], v155 offset:4096
	ds_read_b128 v[206:209], v155 offset:5120
	ds_read_b128 v[210:213], v155 offset:6144
	ds_read_b128 v[214:217], v155 offset:7168
	global_load_lds_dwordx4 v[218:219], off
	v_lshl_add_u64 v[218:219], s[34:35], 0, v[138:139]
	s_add_i32 m0, s31, 0xe000
	s_nop 0
	global_load_lds_dwordx4 v[218:219], off
	s_waitcnt vmcnt(8)
	s_waitcnt lgkmcnt(0)
	s_barrier
	s_setprio 1
	v_mfma_f32_16x16x32_bf16 v[124:127], v[144:147], v[184:187], v[124:127]
	v_mfma_f32_16x16x32_bf16 v[120:123], v[160:163], v[184:187], v[120:123]
	v_mfma_f32_16x16x32_bf16 v[108:111], v[144:147], v[192:195], v[108:111]
	v_mfma_f32_16x16x32_bf16 v[104:107], v[160:163], v[192:195], v[104:107]
	v_mfma_f32_16x16x32_bf16 v[92:95], v[144:147], v[202:205], v[92:95]
	v_mfma_f32_16x16x32_bf16 v[88:91], v[160:163], v[202:205], v[88:91]
	v_mfma_f32_16x16x32_bf16 v[76:79], v[144:147], v[210:213], v[76:79]
	v_mfma_f32_16x16x32_bf16 v[72:75], v[160:163], v[210:213], v[72:75]
	v_mfma_f32_16x16x32_bf16 v[124:127], v[156:159], v[188:191], v[124:127]
	v_mfma_f32_16x16x32_bf16 v[120:123], v[164:167], v[188:191], v[120:123]
	v_mfma_f32_16x16x32_bf16 v[108:111], v[156:159], v[196:199], v[108:111]
	v_mfma_f32_16x16x32_bf16 v[104:107], v[164:167], v[196:199], v[104:107]
	v_mfma_f32_16x16x32_bf16 v[92:95], v[156:159], v[206:209], v[92:95]
	v_mfma_f32_16x16x32_bf16 v[88:91], v[164:167], v[206:209], v[88:91]
	v_mfma_f32_16x16x32_bf16 v[76:79], v[156:159], v[214:217], v[76:79]
	v_mfma_f32_16x16x32_bf16 v[72:75], v[164:167], v[214:217], v[72:75]
	v_mfma_f32_16x16x32_bf16 v[116:119], v[168:171], v[184:187], v[116:119]
	v_mfma_f32_16x16x32_bf16 v[112:115], v[176:179], v[184:187], v[112:115]
	v_mfma_f32_16x16x32_bf16 v[100:103], v[168:171], v[192:195], v[100:103]
	v_mfma_f32_16x16x32_bf16 v[96:99], v[176:179], v[192:195], v[96:99]
	v_mfma_f32_16x16x32_bf16 v[84:87], v[168:171], v[202:205], v[84:87]
	v_mfma_f32_16x16x32_bf16 v[80:83], v[176:179], v[202:205], v[80:83]
	v_mfma_f32_16x16x32_bf16 v[68:71], v[168:171], v[210:213], v[68:71]
	v_mfma_f32_16x16x32_bf16 v[64:67], v[176:179], v[210:213], v[64:67]
	v_mfma_f32_16x16x32_bf16 v[116:119], v[172:175], v[188:191], v[116:119]
	v_mfma_f32_16x16x32_bf16 v[112:115], v[180:183], v[188:191], v[112:115]
	v_mfma_f32_16x16x32_bf16 v[100:103], v[172:175], v[196:199], v[100:103]
	v_mfma_f32_16x16x32_bf16 v[96:99], v[180:183], v[196:199], v[96:99]
	v_mfma_f32_16x16x32_bf16 v[84:87], v[172:175], v[206:209], v[84:87]
	v_mfma_f32_16x16x32_bf16 v[80:83], v[180:183], v[206:209], v[80:83]
	v_mfma_f32_16x16x32_bf16 v[68:71], v[172:175], v[214:217], v[68:71]
	v_mfma_f32_16x16x32_bf16 v[64:67], v[180:183], v[214:217], v[64:67]
	s_setprio 0
	s_barrier
	s_add_i32 s58, s49, s33
	v_lshl_add_u64 v[218:219], s[36:37], 0, v[130:131]
	s_mov_b32 m0, s58
	ds_read_b128 v[184:187], v155 offset:16384
	ds_read_b128 v[188:191], v155 offset:17408
	ds_read_b128 v[192:195], v155 offset:18432
	ds_read_b128 v[196:199], v155 offset:19456
	ds_read_b128 v[202:205], v155 offset:20480
	ds_read_b128 v[206:209], v155 offset:21504
	ds_read_b128 v[210:213], v155 offset:22528
	ds_read_b128 v[214:217], v155 offset:23552
	global_load_lds_dwordx4 v[218:219], off
	s_add_i32 m0, s58, 0x2000
	s_add_u32 s58, s36, 0x100000
	v_lshl_add_u64 v[220:221], s[36:37], 0, v[134:135]
	s_addc_u32 s59, s37, 0
	s_add_i32 s60, s50, s33
	global_load_lds_dwordx4 v[220:221], off
	v_lshl_add_u64 v[222:223], s[58:59], 0, v[130:131]
	s_mov_b32 m0, s60
	v_lshl_add_u64 v[224:225], s[38:39], 0, v[132:133]
	global_load_lds_dwordx4 v[222:223], off
	v_lshl_add_u64 v[222:223], s[58:59], 0, v[134:135]
	s_add_i32 m0, s60, 0x2000
	s_nop 0
	global_load_lds_dwordx4 v[222:223], off
	v_lshl_add_u64 v[222:223], s[38:39], 0, v[128:129]
	s_mov_b32 m0, s31
	s_nop 0
	global_load_lds_dwordx4 v[222:223], off
	s_mov_b32 m0, s42
	s_nop 0
	global_load_lds_dwordx4 v[224:225], off
	s_waitcnt vmcnt(8)
	s_waitcnt lgkmcnt(0)
	s_barrier
	s_setprio 1
	v_mfma_f32_16x16x32_bf16 v[60:63], v[144:147], v[184:187], v[60:63]
	v_mfma_f32_16x16x32_bf16 v[56:59], v[160:163], v[184:187], v[56:59]
	v_mfma_f32_16x16x32_bf16 v[44:47], v[144:147], v[192:195], v[44:47]
	v_mfma_f32_16x16x32_bf16 v[40:43], v[160:163], v[192:195], v[40:43]
	v_mfma_f32_16x16x32_bf16 v[28:31], v[144:147], v[202:205], v[28:31]
	v_mfma_f32_16x16x32_bf16 v[24:27], v[160:163], v[202:205], v[24:27]
	v_mfma_f32_16x16x32_bf16 v[12:15], v[144:147], v[210:213], v[12:15]
	v_mfma_f32_16x16x32_bf16 v[8:11], v[160:163], v[210:213], v[8:11]
	v_mfma_f32_16x16x32_bf16 v[60:63], v[156:159], v[188:191], v[60:63]
	v_mfma_f32_16x16x32_bf16 v[56:59], v[164:167], v[188:191], v[56:59]
	v_mfma_f32_16x16x32_bf16 v[44:47], v[156:159], v[196:199], v[44:47]
	v_mfma_f32_16x16x32_bf16 v[40:43], v[164:167], v[196:199], v[40:43]
	v_mfma_f32_16x16x32_bf16 v[28:31], v[156:159], v[206:209], v[28:31]
	v_mfma_f32_16x16x32_bf16 v[24:27], v[164:167], v[206:209], v[24:27]
	v_mfma_f32_16x16x32_bf16 v[12:15], v[156:159], v[214:217], v[12:15]
	v_mfma_f32_16x16x32_bf16 v[8:11], v[164:167], v[214:217], v[8:11]
	v_mfma_f32_16x16x32_bf16 v[52:55], v[168:171], v[184:187], v[52:55]
	v_mfma_f32_16x16x32_bf16 v[48:51], v[176:179], v[184:187], v[48:51]
	v_mfma_f32_16x16x32_bf16 v[36:39], v[168:171], v[192:195], v[36:39]
	v_mfma_f32_16x16x32_bf16 v[32:35], v[176:179], v[192:195], v[32:35]
	v_mfma_f32_16x16x32_bf16 v[20:23], v[168:171], v[202:205], v[20:23]
	v_mfma_f32_16x16x32_bf16 v[16:19], v[176:179], v[202:205], v[16:19]
	v_mfma_f32_16x16x32_bf16 v[4:7], v[168:171], v[210:213], v[4:7]
	v_mfma_f32_16x16x32_bf16 v[0:3], v[176:179], v[210:213], v[0:3]
	v_mfma_f32_16x16x32_bf16 v[52:55], v[172:175], v[188:191], v[52:55]
	v_mfma_f32_16x16x32_bf16 v[48:51], v[180:183], v[188:191], v[48:51]
	v_mfma_f32_16x16x32_bf16 v[36:39], v[172:175], v[196:199], v[36:39]
	v_mfma_f32_16x16x32_bf16 v[32:35], v[180:183], v[196:199], v[32:35]
	v_mfma_f32_16x16x32_bf16 v[20:23], v[172:175], v[206:209], v[20:23]
	v_mfma_f32_16x16x32_bf16 v[16:19], v[180:183], v[206:209], v[16:19]
	v_mfma_f32_16x16x32_bf16 v[4:7], v[172:175], v[214:217], v[4:7]
	v_mfma_f32_16x16x32_bf16 v[0:3], v[180:183], v[214:217], v[0:3]
	s_setprio 0
	s_barrier
	s_add_i32 s58, 0, 0x18000
	s_add_i32 s59, 0, 0x1c000
	v_add_u32_e32 v164, s58, v151
	v_add_u32_e32 v180, s59, v151
	ds_read_b128 v[144:147], v164
	ds_read_b128 v[156:159], v164 offset:1024
	ds_read_b128 v[160:163], v164 offset:2048
	ds_read_b128 v[164:167], v164 offset:3072
	ds_read_b128 v[168:171], v180
	ds_read_b128 v[172:175], v180 offset:1024
	ds_read_b128 v[176:179], v180 offset:2048
	ds_read_b128 v[180:183], v180 offset:3072
	s_add_u32 s38, s38, 0x100000
	s_addc_u32 s39, s39, 0
	s_mov_b32 m0, s43
	v_lshl_add_u64 v[226:227], s[38:39], 0, v[128:129]
	ds_read_b128 v[184:187], v155 offset:32768
	ds_read_b128 v[188:191], v155 offset:33792
	ds_read_b128 v[192:195], v155 offset:34816
	ds_read_b128 v[196:199], v155 offset:35840
	ds_read_b128 v[202:205], v155 offset:36864
	ds_read_b128 v[206:209], v155 offset:37888
	ds_read_b128 v[210:213], v155 offset:38912
	ds_read_b128 v[214:217], v155 offset:39936
	global_load_lds_dwordx4 v[226:227], off
	v_lshl_add_u64 v[226:227], s[38:39], 0, v[132:133]
	s_mov_b32 m0, s44
	s_nop 0
	global_load_lds_dwordx4 v[226:227], off
	s_waitcnt vmcnt(8)
	s_waitcnt lgkmcnt(0)
	s_barrier
	s_setprio 1
	v_mfma_f32_16x16x32_bf16 v[124:127], v[144:147], v[184:187], v[124:127]
	v_mfma_f32_16x16x32_bf16 v[120:123], v[160:163], v[184:187], v[120:123]
	v_mfma_f32_16x16x32_bf16 v[108:111], v[144:147], v[192:195], v[108:111]
	v_mfma_f32_16x16x32_bf16 v[104:107], v[160:163], v[192:195], v[104:107]
	v_mfma_f32_16x16x32_bf16 v[92:95], v[144:147], v[202:205], v[92:95]
	v_mfma_f32_16x16x32_bf16 v[88:91], v[160:163], v[202:205], v[88:91]
	v_mfma_f32_16x16x32_bf16 v[76:79], v[144:147], v[210:213], v[76:79]
	v_mfma_f32_16x16x32_bf16 v[72:75], v[160:163], v[210:213], v[72:75]
	v_mfma_f32_16x16x32_bf16 v[124:127], v[156:159], v[188:191], v[124:127]
	v_mfma_f32_16x16x32_bf16 v[120:123], v[164:167], v[188:191], v[120:123]
	v_mfma_f32_16x16x32_bf16 v[108:111], v[156:159], v[196:199], v[108:111]
	v_mfma_f32_16x16x32_bf16 v[104:107], v[164:167], v[196:199], v[104:107]
	v_mfma_f32_16x16x32_bf16 v[92:95], v[156:159], v[206:209], v[92:95]
	v_mfma_f32_16x16x32_bf16 v[88:91], v[164:167], v[206:209], v[88:91]
	v_mfma_f32_16x16x32_bf16 v[76:79], v[156:159], v[214:217], v[76:79]
	v_mfma_f32_16x16x32_bf16 v[72:75], v[164:167], v[214:217], v[72:75]
	v_mfma_f32_16x16x32_bf16 v[116:119], v[168:171], v[184:187], v[116:119]
	v_mfma_f32_16x16x32_bf16 v[112:115], v[176:179], v[184:187], v[112:115]
	v_mfma_f32_16x16x32_bf16 v[100:103], v[168:171], v[192:195], v[100:103]
	v_mfma_f32_16x16x32_bf16 v[96:99], v[176:179], v[192:195], v[96:99]
	v_mfma_f32_16x16x32_bf16 v[84:87], v[168:171], v[202:205], v[84:87]
	v_mfma_f32_16x16x32_bf16 v[80:83], v[176:179], v[202:205], v[80:83]
	v_mfma_f32_16x16x32_bf16 v[68:71], v[168:171], v[210:213], v[68:71]
	v_mfma_f32_16x16x32_bf16 v[64:67], v[176:179], v[210:213], v[64:67]
	v_mfma_f32_16x16x32_bf16 v[116:119], v[172:175], v[188:191], v[116:119]
	v_mfma_f32_16x16x32_bf16 v[112:115], v[180:183], v[188:191], v[112:115]
	v_mfma_f32_16x16x32_bf16 v[100:103], v[172:175], v[196:199], v[100:103]
	v_mfma_f32_16x16x32_bf16 v[96:99], v[180:183], v[196:199], v[96:99]
	v_mfma_f32_16x16x32_bf16 v[84:87], v[172:175], v[206:209], v[84:87]
	v_mfma_f32_16x16x32_bf16 v[80:83], v[180:183], v[206:209], v[80:83]
	v_mfma_f32_16x16x32_bf16 v[68:71], v[172:175], v[214:217], v[68:71]
	v_mfma_f32_16x16x32_bf16 v[64:67], v[180:183], v[214:217], v[64:67]
	s_setprio 0
	s_barrier
	s_add_i32 s38, s58, s33
	v_lshl_add_u64 v[218:219], v[218:219], 0, s[4:5]
	s_mov_b32 m0, s38
	ds_read_b128 v[184:187], v155 offset:49152
	ds_read_b128 v[188:191], v155 offset:50176
	ds_read_b128 v[192:195], v155 offset:51200
	ds_read_b128 v[196:199], v155 offset:52224
	ds_read_b128 v[202:205], v155 offset:53248
	ds_read_b128 v[206:209], v155 offset:54272
	ds_read_b128 v[210:213], v155 offset:55296
	ds_read_b128 v[214:217], v155 offset:56320
	global_load_lds_dwordx4 v[218:219], off
	s_add_i32 m0, s38, 0x2000
	s_add_u32 s36, s36, 0x100080
	v_lshl_add_u64 v[218:219], v[220:221], 0, s[4:5]
	s_addc_u32 s37, s37, 0
	s_add_i32 s38, s59, s33
	global_load_lds_dwordx4 v[218:219], off
	v_lshl_add_u64 v[218:219], s[36:37], 0, v[130:131]
	s_mov_b32 m0, s38
	s_nop 0
	global_load_lds_dwordx4 v[218:219], off
	v_lshl_add_u64 v[218:219], s[36:37], 0, v[134:135]
	s_add_i32 m0, s38, 0x2000
	s_nop 0
	global_load_lds_dwordx4 v[218:219], off
	v_lshl_add_u64 v[218:219], v[222:223], 0, s[4:5]
	s_mov_b32 m0, s46
	s_nop 0
	global_load_lds_dwordx4 v[218:219], off
	v_lshl_add_u64 v[218:219], v[224:225], 0, s[4:5]
	s_mov_b32 m0, s47
	s_nop 0
	global_load_lds_dwordx4 v[218:219], off
	s_waitcnt vmcnt(8)
	s_waitcnt lgkmcnt(0)
	s_barrier
	s_setprio 1
	v_mfma_f32_16x16x32_bf16 v[60:63], v[144:147], v[184:187], v[60:63]
	v_mfma_f32_16x16x32_bf16 v[56:59], v[160:163], v[184:187], v[56:59]
	v_mfma_f32_16x16x32_bf16 v[44:47], v[144:147], v[192:195], v[44:47]
	v_mfma_f32_16x16x32_bf16 v[40:43], v[160:163], v[192:195], v[40:43]
	v_mfma_f32_16x16x32_bf16 v[28:31], v[144:147], v[202:205], v[28:31]
	v_mfma_f32_16x16x32_bf16 v[24:27], v[160:163], v[202:205], v[24:27]
	v_mfma_f32_16x16x32_bf16 v[12:15], v[144:147], v[210:213], v[12:15]
	v_mfma_f32_16x16x32_bf16 v[8:11], v[160:163], v[210:213], v[8:11]
	v_mfma_f32_16x16x32_bf16 v[60:63], v[156:159], v[188:191], v[60:63]
	v_mfma_f32_16x16x32_bf16 v[56:59], v[164:167], v[188:191], v[56:59]
	v_mfma_f32_16x16x32_bf16 v[44:47], v[156:159], v[196:199], v[44:47]
	v_mfma_f32_16x16x32_bf16 v[40:43], v[164:167], v[196:199], v[40:43]
	v_mfma_f32_16x16x32_bf16 v[28:31], v[156:159], v[206:209], v[28:31]
	v_mfma_f32_16x16x32_bf16 v[24:27], v[164:167], v[206:209], v[24:27]
	v_mfma_f32_16x16x32_bf16 v[12:15], v[156:159], v[214:217], v[12:15]
	v_mfma_f32_16x16x32_bf16 v[8:11], v[164:167], v[214:217], v[8:11]
	v_mfma_f32_16x16x32_bf16 v[52:55], v[168:171], v[184:187], v[52:55]
	v_mfma_f32_16x16x32_bf16 v[48:51], v[176:179], v[184:187], v[48:51]
	v_mfma_f32_16x16x32_bf16 v[36:39], v[168:171], v[192:195], v[36:39]
	v_mfma_f32_16x16x32_bf16 v[32:35], v[176:179], v[192:195], v[32:35]
	v_mfma_f32_16x16x32_bf16 v[20:23], v[168:171], v[202:205], v[20:23]
	v_mfma_f32_16x16x32_bf16 v[16:19], v[176:179], v[202:205], v[16:19]
	v_mfma_f32_16x16x32_bf16 v[4:7], v[168:171], v[210:213], v[4:7]
	v_mfma_f32_16x16x32_bf16 v[0:3], v[176:179], v[210:213], v[0:3]
	v_mfma_f32_16x16x32_bf16 v[52:55], v[172:175], v[188:191], v[52:55]
	v_mfma_f32_16x16x32_bf16 v[48:51], v[180:183], v[188:191], v[48:51]
	v_mfma_f32_16x16x32_bf16 v[36:39], v[172:175], v[196:199], v[36:39]
	v_mfma_f32_16x16x32_bf16 v[32:35], v[180:183], v[196:199], v[32:35]
	v_mfma_f32_16x16x32_bf16 v[20:23], v[172:175], v[206:209], v[20:23]
	v_mfma_f32_16x16x32_bf16 v[16:19], v[180:183], v[206:209], v[16:19]
	v_mfma_f32_16x16x32_bf16 v[4:7], v[172:175], v[214:217], v[4:7]
	v_mfma_f32_16x16x32_bf16 v[0:3], v[180:183], v[214:217], v[0:3]
	s_setprio 0
	s_barrier
	s_add_i32 s57, s57, 2
	s_add_u32 s34, s34, 0x100
	s_addc_u32 s35, s35, 0
	s_add_u32 s55, s55, 0x100
	s_addc_u32 s56, s56, 0
	s_cmp_gt_u32 s57, 61
	s_cbranch_scc0 .LBB0_1299
	s_and_b64 vcc, exec, s[6:7]
	s_cbranch_vccz .LBB0_1302
	s_barrier

.LBB0_1409:
	ds_read_b128 v[128:131], v177
	ds_read_b128 v[146:149], v177 offset:1024
	ds_read_b128 v[150:153], v177 offset:2048
	ds_read_b128 v[154:157], v177 offset:3072
	ds_read_b128 v[158:161], v178
	ds_read_b128 v[162:165], v178 offset:1024
	ds_read_b128 v[166:169], v178 offset:2048
	ds_read_b128 v[170:173], v178 offset:3072
	s_add_i32 s70, s46, 2
	s_add_u32 s44, s42, 0x100
	s_addc_u32 s45, s43, 0
	s_cmp_eq_u32 s37, s46
	s_cselect_b32 s46, s40, s68
	s_cselect_b32 s49, s39, s45
	s_cselect_b32 s48, s38, s44
	s_cselect_b32 s47, s41, s69
	v_lshl_add_u64 v[214:215], s[42:43], 0, v[140:141]
	s_add_i32 m0, s50, 0xc000
	ds_read_b128 v[180:183], v179
	ds_read_b128 v[184:187], v179 offset:1024
	ds_read_b128 v[188:191], v179 offset:2048
	ds_read_b128 v[192:195], v179 offset:3072
	ds_read_b128 v[196:199], v179 offset:4096
	ds_read_b128 v[202:205], v179 offset:5120
	ds_read_b128 v[206:209], v179 offset:6144
	ds_read_b128 v[210:213], v179 offset:7168
	global_load_lds_dwordx4 v[214:215], off
	v_lshl_add_u64 v[214:215], s[42:43], 0, v[142:143]
	s_add_i32 m0, s50, 0xe000
	s_nop 0
	global_load_lds_dwordx4 v[214:215], off
	s_waitcnt vmcnt(8)
	s_waitcnt lgkmcnt(0)
	s_barrier
	s_setprio 1
	v_mfma_f32_16x16x32_bf16 v[124:127], v[128:131], v[180:183], v[124:127]
	v_mfma_f32_16x16x32_bf16 v[120:123], v[150:153], v[180:183], v[120:123]
	v_mfma_f32_16x16x32_bf16 v[108:111], v[128:131], v[188:191], v[108:111]
	v_mfma_f32_16x16x32_bf16 v[104:107], v[150:153], v[188:191], v[104:107]
	v_mfma_f32_16x16x32_bf16 v[92:95], v[128:131], v[196:199], v[92:95]
	v_mfma_f32_16x16x32_bf16 v[88:91], v[150:153], v[196:199], v[88:91]
	v_mfma_f32_16x16x32_bf16 v[76:79], v[128:131], v[206:209], v[76:79]
	v_mfma_f32_16x16x32_bf16 v[72:75], v[150:153], v[206:209], v[72:75]
	v_mfma_f32_16x16x32_bf16 v[124:127], v[146:149], v[184:187], v[124:127]
	v_mfma_f32_16x16x32_bf16 v[120:123], v[154:157], v[184:187], v[120:123]
	v_mfma_f32_16x16x32_bf16 v[108:111], v[146:149], v[192:195], v[108:111]
	v_mfma_f32_16x16x32_bf16 v[104:107], v[154:157], v[192:195], v[104:107]
	v_mfma_f32_16x16x32_bf16 v[92:95], v[146:149], v[202:205], v[92:95]
	v_mfma_f32_16x16x32_bf16 v[88:91], v[154:157], v[202:205], v[88:91]
	v_mfma_f32_16x16x32_bf16 v[76:79], v[146:149], v[210:213], v[76:79]
	v_mfma_f32_16x16x32_bf16 v[72:75], v[154:157], v[210:213], v[72:75]
	v_mfma_f32_16x16x32_bf16 v[116:119], v[158:161], v[180:183], v[116:119]
	v_mfma_f32_16x16x32_bf16 v[112:115], v[166:169], v[180:183], v[112:115]
	v_mfma_f32_16x16x32_bf16 v[100:103], v[158:161], v[188:191], v[100:103]
	v_mfma_f32_16x16x32_bf16 v[96:99], v[166:169], v[188:191], v[96:99]
	v_mfma_f32_16x16x32_bf16 v[84:87], v[158:161], v[196:199], v[84:87]
	v_mfma_f32_16x16x32_bf16 v[80:83], v[166:169], v[196:199], v[80:83]
	v_mfma_f32_16x16x32_bf16 v[68:71], v[158:161], v[206:209], v[68:71]
	v_mfma_f32_16x16x32_bf16 v[64:67], v[166:169], v[206:209], v[64:67]
	v_mfma_f32_16x16x32_bf16 v[116:119], v[162:165], v[184:187], v[116:119]
	v_mfma_f32_16x16x32_bf16 v[112:115], v[170:173], v[184:187], v[112:115]
	v_mfma_f32_16x16x32_bf16 v[100:103], v[162:165], v[192:195], v[100:103]
	v_mfma_f32_16x16x32_bf16 v[96:99], v[170:173], v[192:195], v[96:99]
	v_mfma_f32_16x16x32_bf16 v[84:87], v[162:165], v[202:205], v[84:87]
	v_mfma_f32_16x16x32_bf16 v[80:83], v[170:173], v[202:205], v[80:83]
	v_mfma_f32_16x16x32_bf16 v[68:71], v[162:165], v[210:213], v[68:71]
	v_mfma_f32_16x16x32_bf16 v[64:67], v[170:173], v[210:213], v[64:67]
	s_setprio 0
	s_barrier
	s_add_i32 s42, s58, s33
	v_lshl_add_u64 v[214:215], s[46:47], 0, v[134:135]
	s_mov_b32 m0, s42
	ds_read_b128 v[180:183], v179 offset:16384
	ds_read_b128 v[184:187], v179 offset:17408
	ds_read_b128 v[188:191], v179 offset:18432
	ds_read_b128 v[192:195], v179 offset:19456
	ds_read_b128 v[196:199], v179 offset:20480
	ds_read_b128 v[202:205], v179 offset:21504
	ds_read_b128 v[206:209], v179 offset:22528
	ds_read_b128 v[210:213], v179 offset:23552
	global_load_lds_dwordx4 v[214:215], off
	s_add_i32 m0, s42, 0x2000
	s_add_u32 s42, s46, 0x2b0000
	v_lshl_add_u64 v[216:217], s[46:47], 0, v[138:139]
	s_addc_u32 s43, s47, 0
	s_add_i32 s71, s59, s33
	global_load_lds_dwordx4 v[216:217], off
	v_lshl_add_u64 v[218:219], s[42:43], 0, v[134:135]
	s_mov_b32 m0, s71
	v_lshl_add_u64 v[220:221], s[48:49], 0, v[136:137]
	global_load_lds_dwordx4 v[218:219], off
	v_lshl_add_u64 v[218:219], s[42:43], 0, v[138:139]
	s_add_i32 m0, s71, 0x2000
	s_nop 0
	global_load_lds_dwordx4 v[218:219], off
	v_lshl_add_u64 v[218:219], s[48:49], 0, v[132:133]
	s_mov_b32 m0, s50
	s_nop 0
	global_load_lds_dwordx4 v[218:219], off
	s_mov_b32 m0, s51
	s_nop 0
	global_load_lds_dwordx4 v[220:221], off
	s_waitcnt vmcnt(8)
	s_waitcnt lgkmcnt(0)
	s_barrier
	s_setprio 1
	v_mfma_f32_16x16x32_bf16 v[60:63], v[128:131], v[180:183], v[60:63]
	v_mfma_f32_16x16x32_bf16 v[56:59], v[150:153], v[180:183], v[56:59]
	v_mfma_f32_16x16x32_bf16 v[44:47], v[128:131], v[188:191], v[44:47]
	v_mfma_f32_16x16x32_bf16 v[40:43], v[150:153], v[188:191], v[40:43]
	v_mfma_f32_16x16x32_bf16 v[28:31], v[128:131], v[196:199], v[28:31]
	v_mfma_f32_16x16x32_bf16 v[24:27], v[150:153], v[196:199], v[24:27]
	v_mfma_f32_16x16x32_bf16 v[12:15], v[128:131], v[206:209], v[12:15]
	v_mfma_f32_16x16x32_bf16 v[8:11], v[150:153], v[206:209], v[8:11]
	v_mfma_f32_16x16x32_bf16 v[60:63], v[146:149], v[184:187], v[60:63]
	v_mfma_f32_16x16x32_bf16 v[56:59], v[154:157], v[184:187], v[56:59]
	v_mfma_f32_16x16x32_bf16 v[44:47], v[146:149], v[192:195], v[44:47]
	v_mfma_f32_16x16x32_bf16 v[40:43], v[154:157], v[192:195], v[40:43]
	v_mfma_f32_16x16x32_bf16 v[28:31], v[146:149], v[202:205], v[28:31]
	v_mfma_f32_16x16x32_bf16 v[24:27], v[154:157], v[202:205], v[24:27]
	v_mfma_f32_16x16x32_bf16 v[12:15], v[146:149], v[210:213], v[12:15]
	v_mfma_f32_16x16x32_bf16 v[8:11], v[154:157], v[210:213], v[8:11]
	v_mfma_f32_16x16x32_bf16 v[52:55], v[158:161], v[180:183], v[52:55]
	v_mfma_f32_16x16x32_bf16 v[48:51], v[166:169], v[180:183], v[48:51]
	v_mfma_f32_16x16x32_bf16 v[36:39], v[158:161], v[188:191], v[36:39]
	v_mfma_f32_16x16x32_bf16 v[32:35], v[166:169], v[188:191], v[32:35]
	v_mfma_f32_16x16x32_bf16 v[20:23], v[158:161], v[196:199], v[20:23]
	v_mfma_f32_16x16x32_bf16 v[16:19], v[166:169], v[196:199], v[16:19]
	v_mfma_f32_16x16x32_bf16 v[4:7], v[158:161], v[206:209], v[4:7]
	v_mfma_f32_16x16x32_bf16 v[0:3], v[166:169], v[206:209], v[0:3]
	v_mfma_f32_16x16x32_bf16 v[52:55], v[162:165], v[184:187], v[52:55]
	v_mfma_f32_16x16x32_bf16 v[48:51], v[170:173], v[184:187], v[48:51]
	v_mfma_f32_16x16x32_bf16 v[36:39], v[162:165], v[192:195], v[36:39]
	v_mfma_f32_16x16x32_bf16 v[32:35], v[170:173], v[192:195], v[32:35]
	v_mfma_f32_16x16x32_bf16 v[20:23], v[162:165], v[202:205], v[20:23]
	v_mfma_f32_16x16x32_bf16 v[16:19], v[170:173], v[202:205], v[16:19]
	v_mfma_f32_16x16x32_bf16 v[4:7], v[162:165], v[210:213], v[4:7]
	v_mfma_f32_16x16x32_bf16 v[0:3], v[170:173], v[210:213], v[0:3]
	s_setprio 0
	s_barrier
	s_add_i32 s71, 0, 0x18000
	s_add_i32 s72, 0, 0x1c000
	v_add_u32_e32 v154, s71, v175
	v_add_u32_e32 v170, s72, v175
	ds_read_b128 v[128:131], v154
	ds_read_b128 v[146:149], v154 offset:1024
	ds_read_b128 v[150:153], v154 offset:2048
	ds_read_b128 v[154:157], v154 offset:3072
	ds_read_b128 v[158:161], v170
	ds_read_b128 v[162:165], v170 offset:1024
	ds_read_b128 v[166:169], v170 offset:2048
	ds_read_b128 v[170:173], v170 offset:3072
	s_add_u32 s42, s48, 0x2b0000
	s_addc_u32 s43, s49, 0
	s_mov_b32 m0, s52
	v_lshl_add_u64 v[222:223], s[42:43], 0, v[132:133]
	ds_read_b128 v[180:183], v179 offset:32768
	ds_read_b128 v[184:187], v179 offset:33792
	ds_read_b128 v[188:191], v179 offset:34816
	ds_read_b128 v[192:195], v179 offset:35840
	ds_read_b128 v[196:199], v179 offset:36864
	ds_read_b128 v[202:205], v179 offset:37888
	ds_read_b128 v[206:209], v179 offset:38912
	ds_read_b128 v[210:213], v179 offset:39936
	global_load_lds_dwordx4 v[222:223], off
	v_lshl_add_u64 v[222:223], s[42:43], 0, v[136:137]
	s_mov_b32 m0, s53
	s_nop 0
	global_load_lds_dwordx4 v[222:223], off
	s_waitcnt vmcnt(8)
	s_waitcnt lgkmcnt(0)
	s_barrier
	s_setprio 1
	v_mfma_f32_16x16x32_bf16 v[124:127], v[128:131], v[180:183], v[124:127]
	v_mfma_f32_16x16x32_bf16 v[120:123], v[150:153], v[180:183], v[120:123]
	v_mfma_f32_16x16x32_bf16 v[108:111], v[128:131], v[188:191], v[108:111]
	v_mfma_f32_16x16x32_bf16 v[104:107], v[150:153], v[188:191], v[104:107]
	v_mfma_f32_16x16x32_bf16 v[92:95], v[128:131], v[196:199], v[92:95]
	v_mfma_f32_16x16x32_bf16 v[88:91], v[150:153], v[196:199], v[88:91]
	v_mfma_f32_16x16x32_bf16 v[76:79], v[128:131], v[206:209], v[76:79]
	v_mfma_f32_16x16x32_bf16 v[72:75], v[150:153], v[206:209], v[72:75]
	v_mfma_f32_16x16x32_bf16 v[124:127], v[146:149], v[184:187], v[124:127]
	v_mfma_f32_16x16x32_bf16 v[120:123], v[154:157], v[184:187], v[120:123]
	v_mfma_f32_16x16x32_bf16 v[108:111], v[146:149], v[192:195], v[108:111]
	v_mfma_f32_16x16x32_bf16 v[104:107], v[154:157], v[192:195], v[104:107]
	v_mfma_f32_16x16x32_bf16 v[92:95], v[146:149], v[202:205], v[92:95]
	v_mfma_f32_16x16x32_bf16 v[88:91], v[154:157], v[202:205], v[88:91]
	v_mfma_f32_16x16x32_bf16 v[76:79], v[146:149], v[210:213], v[76:79]
	v_mfma_f32_16x16x32_bf16 v[72:75], v[154:157], v[210:213], v[72:75]
	v_mfma_f32_16x16x32_bf16 v[116:119], v[158:161], v[180:183], v[116:119]
	v_mfma_f32_16x16x32_bf16 v[112:115], v[166:169], v[180:183], v[112:115]
	v_mfma_f32_16x16x32_bf16 v[100:103], v[158:161], v[188:191], v[100:103]
	v_mfma_f32_16x16x32_bf16 v[96:99], v[166:169], v[188:191], v[96:99]
	v_mfma_f32_16x16x32_bf16 v[84:87], v[158:161], v[196:199], v[84:87]
	v_mfma_f32_16x16x32_bf16 v[80:83], v[166:169], v[196:199], v[80:83]
	v_mfma_f32_16x16x32_bf16 v[68:71], v[158:161], v[206:209], v[68:71]
	v_mfma_f32_16x16x32_bf16 v[64:67], v[166:169], v[206:209], v[64:67]
	v_mfma_f32_16x16x32_bf16 v[116:119], v[162:165], v[184:187], v[116:119]
	v_mfma_f32_16x16x32_bf16 v[112:115], v[170:173], v[184:187], v[112:115]
	v_mfma_f32_16x16x32_bf16 v[100:103], v[162:165], v[192:195], v[100:103]
	v_mfma_f32_16x16x32_bf16 v[96:99], v[170:173], v[192:195], v[96:99]
	v_mfma_f32_16x16x32_bf16 v[84:87], v[162:165], v[202:205], v[84:87]
	v_mfma_f32_16x16x32_bf16 v[80:83], v[170:173], v[202:205], v[80:83]
	v_mfma_f32_16x16x32_bf16 v[68:71], v[162:165], v[210:213], v[68:71]
	v_mfma_f32_16x16x32_bf16 v[64:67], v[170:173], v[210:213], v[64:67]
	s_setprio 0
	s_barrier
	s_add_i32 s42, s71, s33
	v_lshl_add_u64 v[214:215], v[214:215], 0, s[10:11]
	s_mov_b32 m0, s42
	ds_read_b128 v[180:183], v179 offset:49152
	ds_read_b128 v[184:187], v179 offset:50176
	ds_read_b128 v[188:191], v179 offset:51200
	ds_read_b128 v[192:195], v179 offset:52224
	ds_read_b128 v[196:199], v179 offset:53248
	ds_read_b128 v[202:205], v179 offset:54272
	ds_read_b128 v[206:209], v179 offset:55296
	ds_read_b128 v[210:213], v179 offset:56320
	global_load_lds_dwordx4 v[214:215], off
	s_add_i32 m0, s42, 0x2000
	s_add_u32 s42, s46, 0x2b0080
	v_lshl_add_u64 v[214:215], v[216:217], 0, s[10:11]
	s_addc_u32 s43, s47, 0
	s_add_i32 s46, s72, s33
	global_load_lds_dwordx4 v[214:215], off
	v_lshl_add_u64 v[214:215], s[42:43], 0, v[134:135]
	s_mov_b32 m0, s46
	s_nop 0
	global_load_lds_dwordx4 v[214:215], off
	v_lshl_add_u64 v[214:215], s[42:43], 0, v[138:139]
	s_add_i32 m0, s46, 0x2000
	s_nop 0
	global_load_lds_dwordx4 v[214:215], off
	v_lshl_add_u64 v[214:215], v[218:219], 0, s[10:11]
	s_mov_b32 m0, s54
	s_nop 0
	global_load_lds_dwordx4 v[214:215], off
	v_lshl_add_u64 v[214:215], v[220:221], 0, s[10:11]
	s_mov_b32 m0, s55
	s_nop 0
	global_load_lds_dwordx4 v[214:215], off
	s_waitcnt vmcnt(8)
	s_waitcnt lgkmcnt(0)
	s_barrier
	s_setprio 1
	v_mfma_f32_16x16x32_bf16 v[60:63], v[128:131], v[180:183], v[60:63]
	v_mfma_f32_16x16x32_bf16 v[56:59], v[150:153], v[180:183], v[56:59]
	v_mfma_f32_16x16x32_bf16 v[44:47], v[128:131], v[188:191], v[44:47]
	v_mfma_f32_16x16x32_bf16 v[40:43], v[150:153], v[188:191], v[40:43]
	v_mfma_f32_16x16x32_bf16 v[28:31], v[128:131], v[196:199], v[28:31]
	v_mfma_f32_16x16x32_bf16 v[24:27], v[150:153], v[196:199], v[24:27]
	v_mfma_f32_16x16x32_bf16 v[12:15], v[128:131], v[206:209], v[12:15]
	v_mfma_f32_16x16x32_bf16 v[8:11], v[150:153], v[206:209], v[8:11]
	v_mfma_f32_16x16x32_bf16 v[60:63], v[146:149], v[184:187], v[60:63]
	v_mfma_f32_16x16x32_bf16 v[56:59], v[154:157], v[184:187], v[56:59]
	v_mfma_f32_16x16x32_bf16 v[44:47], v[146:149], v[192:195], v[44:47]
	v_mfma_f32_16x16x32_bf16 v[40:43], v[154:157], v[192:195], v[40:43]
	v_mfma_f32_16x16x32_bf16 v[28:31], v[146:149], v[202:205], v[28:31]
	v_mfma_f32_16x16x32_bf16 v[24:27], v[154:157], v[202:205], v[24:27]
	v_mfma_f32_16x16x32_bf16 v[12:15], v[146:149], v[210:213], v[12:15]
	v_mfma_f32_16x16x32_bf16 v[8:11], v[154:157], v[210:213], v[8:11]
	v_mfma_f32_16x16x32_bf16 v[52:55], v[158:161], v[180:183], v[52:55]
	v_mfma_f32_16x16x32_bf16 v[48:51], v[166:169], v[180:183], v[48:51]
	v_mfma_f32_16x16x32_bf16 v[36:39], v[158:161], v[188:191], v[36:39]
	v_mfma_f32_16x16x32_bf16 v[32:35], v[166:169], v[188:191], v[32:35]
	v_mfma_f32_16x16x32_bf16 v[20:23], v[158:161], v[196:199], v[20:23]
	v_mfma_f32_16x16x32_bf16 v[16:19], v[166:169], v[196:199], v[16:19]
	v_mfma_f32_16x16x32_bf16 v[4:7], v[158:161], v[206:209], v[4:7]
	v_mfma_f32_16x16x32_bf16 v[0:3], v[166:169], v[206:209], v[0:3]
	v_mfma_f32_16x16x32_bf16 v[52:55], v[162:165], v[184:187], v[52:55]
	v_mfma_f32_16x16x32_bf16 v[48:51], v[170:173], v[184:187], v[48:51]
	v_mfma_f32_16x16x32_bf16 v[36:39], v[162:165], v[192:195], v[36:39]
	v_mfma_f32_16x16x32_bf16 v[32:35], v[170:173], v[192:195], v[32:35]
	v_mfma_f32_16x16x32_bf16 v[20:23], v[162:165], v[202:205], v[20:23]
	v_mfma_f32_16x16x32_bf16 v[16:19], v[170:173], v[202:205], v[16:19]
	v_mfma_f32_16x16x32_bf16 v[4:7], v[162:165], v[210:213], v[4:7]
	v_mfma_f32_16x16x32_bf16 v[0:3], v[170:173], v[210:213], v[0:3]
	s_setprio 0
	s_barrier
	s_add_u32 s68, s68, 0x100
	s_addc_u32 s69, s69, 0
	s_cmp_ge_i32 s70, s67
	s_mov_b64 s[42:43], s[44:45]
	s_mov_b32 s46, s70
	s_cbranch_scc0 .LBB0_1409
	s_and_b64 vcc, exec, s[14:15]
	s_cbranch_vccz .LBB0_1412
